# P7 rstd loads prefetched 3 row-groups ahead + P2 EpiRes residual loads prefetched 3 row-groups ahead (counted vmcnt)
# baseline (speedup 1.0000x reference)
; __device__ __forceinline__ unsigned cvt_pk_bf16(float lo, float hi) { unsigned r; asm volatile("v_cvt_pk_bf16_f32 %0, %1, %2" : "=v"(r) : "v"(lo), "v"(hi)); return r; }
;     __device__ __forceinline__ void operator()(const f32x4 (&acc)[2][2][4][2], const Unit& u, int wr, int wc, int fr, int fq) const {
;     ...
;         for (int ai = 0; ai < 2; ++ai)
; #pragma unroll
;             for (int m = 0; m < 4; ++m) {
;                 const int row = row0 + ai * HALF + m * 16;
;                 const float* xr = (row < M_P) ? xin_p + (size_t)row * DM : xin_s + (size_t)(row - M_P) * DM;
;                 float* orow = out + (size_t)row * DM;
;                 float ss = 0.f;
; #pragma unroll
;                 for (int bj = 0; bj < 2; ++bj) {
;                     f32x4 o[2];
; #pragma unroll
;                     for (int n = 0; n < 2; ++n) { const f32x4 xv = *(const f32x4*)(xr + col0 + bj * HALF + 4 * n); o[n] = xv + acc[ai][bj][m][n] * (0.5f * ALPHA2); *(f32x4*)(orow + col0 + bj * HALF + 4 * n) = o[n]; }
;                     if constexpr (WX) {
; #pragma unroll
;                         for (int n = 0; n < 2; ++n) ss += (o[n][0] * o[n][0] + o[n][1] * o[n][1]) + (o[n][2] * o[n][2] + o[n][3] * o[n][3]);
;                         const f32x4 a = o[0] * gv[bj][0], b = o[1] * gv[bj][1];
;                         u32x4 w; w.x = cvt_pk_bf16(a[0], a[1]); w.y = cvt_pk_bf16(a[2], a[3]); w.z = cvt_pk_bf16(b[0], b[1]); w.w = cvt_pk_bf16(b[2], b[3]);
;                         *(u32x4*)(xn + (size_t)row * DM + col0 + bj * HALF) = w;
.LBB0_384:
	v_lshl_or_b32 v162, s33, 8, v172
	v_ashrrev_i32_e32 v163, 31, v162
	v_lshl_add_u64 v[60:61], v[162:163], 2, s[80:81]
	global_load_dwordx4 v[68:71], v[60:61], off offset:16
	global_load_dwordx4 v[72:75], v[60:61], off
	global_load_dwordx4 v[56:59], v[60:61], off offset:528
	s_nop 0
	global_load_dwordx4 v[60:63], v[60:61], off offset:512
	v_lshl_add_u32 v164, s16, 8, v170
	v_cmp_lt_i32_e32 vcc, s84, v164
	s_and_saveexec_b64 s[16:17], vcc
	s_xor_b64 s[16:17], exec, s[16:17]
	v_add_u32_e32 v152, 0xffffc000, v164
	v_lshlrev_b64 v[166:167], 12, v[152:153]
	v_lshl_add_u64 v[168:169], s[70:71], 0, v[166:167]
	v_mov_b32_e32 v165, v153
	s_andn2_saveexec_b64 s[16:17], s[16:17]
	v_ashrrev_i32_e32 v165, 31, v164
	v_lshlrev_b64 v[166:167], 12, v[164:165]
	v_lshl_add_u64 v[168:169], s[68:69], 0, v[166:167]
	s_or_b64 exec, exec, s[16:17]
	v_lshlrev_b64 v[166:167], 2, v[162:163]
	v_lshl_add_u64 v[168:169], v[168:169], 0, v[166:167]
	v_mov_b32_e32 v204, v168
	v_mov_b32_e32 v205, v169
	v_mov_b32_e32 v254, 0x10000
	v_mov_b32_e32 v255, 0
	v_lshl_add_u64 v[208:209], v[254:255], 0, v[204:205]
	global_load_dwordx4 v[216:219], v[208:209], off
	global_load_dwordx4 v[220:223], v[208:209], off offset:16
	global_load_dwordx4 v[224:227], v[208:209], off offset:512
	global_load_dwordx4 v[228:231], v[208:209], off offset:528
	v_mov_b32_e32 v254, 0x20000
	v_mov_b32_e32 v255, 0
	v_lshl_add_u64 v[208:209], v[254:255], 0, v[204:205]
	global_load_dwordx4 v[232:235], v[208:209], off
	global_load_dwordx4 v[236:239], v[208:209], off offset:16
	global_load_dwordx4 v[242:245], v[208:209], off offset:512
	global_load_dwordx4 v[246:249], v[208:209], off offset:528
	v_mov_b32_e32 v254, 0x30000
	v_mov_b32_e32 v255, 0
	v_lshl_add_u64 v[208:209], v[254:255], 0, v[204:205]
	global_load_dwordx4 v[192:195], v[208:209], off
	global_load_dwordx4 v[196:199], v[208:209], off offset:16
	global_load_dwordx4 v[200:203], v[208:209], off offset:512
	global_load_dwordx4 v[212:215], v[208:209], off offset:528
	global_load_dwordx4 v[178:181], v[168:169], off
	v_lshlrev_b64 v[182:183], 12, v[164:165]
	v_lshl_add_u64 v[182:183], s[22:23], 0, v[182:183]
	v_lshl_add_u64 v[186:187], v[182:183], 0, v[166:167]
	v_lshlrev_b64 v[182:183], 11, v[164:165]
	v_lshl_add_u64 v[182:183], s[72:73], 0, v[182:183]
	v_lshl_add_u64 v[188:189], v[162:163], 1, v[182:183]
	s_mul_hi_i32 s43, s33, 0xc000
	s_mul_i32 s42, s33, 0xc000
	s_waitcnt vmcnt(0)
	v_pk_fma_f32 v[142:143], v[142:143], 0.5, v[180:181] op_sel_hi:[1,0,1]
	v_pk_fma_f32 v[140:141], v[140:141], 0.5, v[178:179] op_sel_hi:[1,0,1]
	global_store_dwordx4 v[186:187], v[140:143], off
	global_load_dwordx4 v[178:181], v[168:169], off offset:16
	v_pk_mul_f32 v[182:183], v[74:75], v[142:143]
	v_pk_mul_f32 v[184:185], v[72:73], v[140:141]
	s_waitcnt vmcnt(0)
	v_pk_fma_f32 v[136:137], v[136:137], 0.5, v[178:179] op_sel_hi:[1,0,1]
	v_pk_fma_f32 v[138:139], v[138:139], 0.5, v[180:181] op_sel_hi:[1,0,1]
	v_pk_mul_f32 v[180:181], v[68:69], v[136:137]
	global_store_dwordx4 v[186:187], v[136:139], off offset:16
	v_pk_mul_f32 v[190:191], v[70:71], v[138:139]
	v_cvt_pk_bf16_f32 v178, v184, v185
	v_cvt_pk_bf16_f32 v179, v182, v183
	v_cvt_pk_bf16_f32 v180, v180, v181
	s_nop 0
	v_cvt_pk_bf16_f32 v181, v190, v191
	global_store_dwordx4 v[188:189], v[178:181], off
	global_load_dwordx4 v[178:181], v[168:169], off offset:512
	s_waitcnt vmcnt(0)
	v_pk_fma_f32 v[180:181], v[134:135], 0.5, v[180:181] op_sel_hi:[1,0,1]
	v_pk_fma_f32 v[178:179], v[132:133], 0.5, v[178:179] op_sel_hi:[1,0,1]
	global_store_dwordx4 v[186:187], v[178:181], off offset:512
	global_load_dwordx4 v[182:185], v[168:169], off offset:528
	v_and_b32_e32 v133, 64, v176
	v_xor_b32_e32 v132, 16, v176
	v_add_u32_e32 v133, 64, v133
	v_xor_b32_e32 v134, 32, v176
	v_cmp_lt_i32_e32 vcc, v132, v133
	v_mul_f32_e32 v135, v143, v143
	v_fmac_f32_e32 v135, v142, v142
	v_cndmask_b32_e32 v132, v176, v132, vcc
	v_cmp_lt_i32_e32 vcc, v134, v133
	v_lshlrev_b32_e32 v132, 2, v132
	s_waitcnt vmcnt(0)
	v_pk_fma_f32 v[130:131], v[130:131], 0.5, v[184:185] op_sel_hi:[1,0,1]
	v_cndmask_b32_e32 v133, v176, v134, vcc
	v_mul_f32_e32 v134, v141, v141
	v_fmac_f32_e32 v134, v140, v140
	v_add_f32_e32 v134, v134, v135
	v_mul_f32_e32 v135, v137, v137
	v_mul_f32_e32 v137, v139, v139
	v_fmac_f32_e32 v135, v136, v136
	v_fmac_f32_e32 v137, v138, v138
	v_mul_f32_e32 v139, v179, v179
	v_mul_f32_e32 v140, v181, v181
	v_add_f32_e32 v135, v135, v137
	v_fmac_f32_e32 v139, v178, v178
	v_fmac_f32_e32 v140, v180, v180
	v_add_f32_e32 v138, v134, v135
	v_add_f32_e32 v139, v139, v140
	v_pk_fma_f32 v[128:129], v[128:129], 0.5, v[182:183] op_sel_hi:[1,0,1]
	v_add_f32_e32 v138, v138, v139
	v_mul_f32_e32 v139, v129, v129
	v_mul_f32_e32 v140, v131, v131
	v_fmac_f32_e32 v139, v128, v128
	v_fmac_f32_e32 v140, v130, v130
	v_add_f32_e32 v139, v139, v140
	v_add_f32_e32 v140, v138, v139
	ds_bpermute_b32 v141, v132, v140
	global_store_dwordx4 v[186:187], v[128:131], off offset:528
	v_pk_mul_f32 v[138:139], v[56:57], v[128:129]
	v_lshlrev_b32_e32 v133, 2, v133
	v_pk_mul_f32 v[136:137], v[62:63], v[180:181]
	s_waitcnt lgkmcnt(0)
	v_add_f32_e32 v128, v140, v141
	ds_bpermute_b32 v129, v133, v128
	v_pk_mul_f32 v[134:135], v[60:61], v[178:179]
	v_pk_mul_f32 v[130:131], v[58:59], v[130:131]
	v_cvt_pk_bf16_f32 v134, v134, v135
	v_cvt_pk_bf16_f32 v135, v136, v137
	v_cvt_pk_bf16_f32 v136, v138, v139
	s_nop 0
	v_cvt_pk_bf16_f32 v137, v130, v131
	global_store_dwordx4 v[188:189], v[134:137], off offset:256
	s_and_saveexec_b64 s[16:17], s[6:7]
	s_cbranch_execz .LBB0_390
	v_lshl_add_u64 v[130:131], v[164:165], 0, s[42:43]
	v_lshl_add_u64 v[130:131], v[130:131], 4, s[20:21]
	s_waitcnt lgkmcnt(0)
	v_add_f32_e32 v128, v128, v129
	global_store_dword v[130:131], v128, off
; __device__ __forceinline__ unsigned cvt_pk_bf16(float lo, float hi) { unsigned r; asm volatile("v_cvt_pk_bf16_f32 %0, %1, %2" : "=v"(r) : "v"(lo), "v"(hi)); return r; }
;     __device__ __forceinline__ void operator()(const f32x4 (&acc)[2][2][4][2], const Unit& u, int wr, int wc, int fr, int fq) const {
;     ...
;             for (int m = 0; m < 4; ++m) {
;                 const int row = row0 + ai * HALF + m * 16;
;                 const float* xr = (row < M_P) ? xin_p + (size_t)row * DM : xin_s + (size_t)(row - M_P) * DM;
;                 float* orow = out + (size_t)row * DM;
;                 float ss = 0.f;
; #pragma unroll
;                 for (int bj = 0; bj < 2; ++bj) {
;                     f32x4 o[2];
; #pragma unroll
;                     for (int n = 0; n < 2; ++n) { const f32x4 xv = *(const f32x4*)(xr + col0 + bj * HALF + 4 * n); o[n] = xv + acc[ai][bj][m][n] * (0.5f * ALPHA2); *(f32x4*)(orow + col0 + bj * HALF + 4 * n) = o[n]; }
;                     if constexpr (WX) {
; #pragma unroll
;                         for (int n = 0; n < 2; ++n) ss += (o[n][0] * o[n][0] + o[n][1] * o[n][1]) + (o[n][2] * o[n][2] + o[n][3] * o[n][3]);
;                         const f32x4 a = o[0] * gv[bj][0], b = o[1] * gv[bj][1];
;                         u32x4 w; w.x = cvt_pk_bf16(a[0], a[1]); w.y = cvt_pk_bf16(a[2], a[3]); w.z = cvt_pk_bf16(b[0], b[1]); w.w = cvt_pk_bf16(b[2], b[3]);
;                         *(u32x4*)(xn + (size_t)row * DM + col0 + bj * HALF) = w;
.LBB0_390:
	s_or_b64 exec, exec, s[16:17]
	s_waitcnt lgkmcnt(0)
	v_or_b32_e32 v128, 16, v164
	v_cmp_lt_i32_e32 vcc, s84, v128
	s_and_saveexec_b64 s[16:17], vcc
	s_xor_b64 s[16:17], exec, s[16:17]
	v_add_u32_e32 v152, 0xffffc010, v164
	v_lshlrev_b64 v[130:131], 12, v[152:153]
	v_lshl_add_u64 v[130:131], s[70:71], 0, v[130:131]
	v_mov_b32_e32 v129, v153
	s_andn2_saveexec_b64 s[16:17], s[16:17]
	v_ashrrev_i32_e32 v129, 31, v128
	v_lshlrev_b64 v[130:131], 12, v[128:129]
	v_lshl_add_u64 v[130:131], s[68:69], 0, v[130:131]
	s_or_b64 exec, exec, s[16:17]
	v_lshl_add_u64 v[130:131], v[130:131], 0, v[166:167]
	v_mov_b32_e32 v254, 0x80000
	v_mov_b32_e32 v255, 0
	v_lshl_add_u64 v[208:209], v[254:255], 0, v[204:205]
	v_lshlrev_b64 v[138:139], 12, v[128:129]
	v_lshl_add_u64 v[138:139], s[22:23], 0, v[138:139]
	v_lshl_add_u64 v[138:139], v[138:139], 0, v[166:167]
	v_lshlrev_b64 v[140:141], 11, v[128:129]
	v_lshl_add_u64 v[140:141], s[72:73], 0, v[140:141]
	v_lshl_add_u64 v[140:141], v[162:163], 1, v[140:141]
	s_waitcnt vmcnt(21)
	v_pk_fma_f32 v[126:127], v[126:127], 0.5, v[218:219] op_sel_hi:[1,0,1]
	v_pk_fma_f32 v[124:125], v[124:125], 0.5, v[216:217] op_sel_hi:[1,0,1]
	global_load_dwordx4 v[216:219], v[208:209], off
	global_store_dwordx4 v[138:139], v[124:127], off
	s_nop 0
	v_pk_mul_f32 v[142:143], v[74:75], v[126:127]
	v_pk_mul_f32 v[168:169], v[72:73], v[124:125]
	v_mul_f32_e32 v125, v125, v125
	v_mul_f32_e32 v127, v127, v127
	v_fmac_f32_e32 v125, v124, v124
	v_fmac_f32_e32 v127, v126, v126
	v_add_f32_e32 v124, v125, v127
	s_waitcnt vmcnt(22)
	v_pk_fma_f32 v[120:121], v[120:121], 0.5, v[220:221] op_sel_hi:[1,0,1]
	v_pk_fma_f32 v[122:123], v[122:123], 0.5, v[222:223] op_sel_hi:[1,0,1]
	global_load_dwordx4 v[220:223], v[208:209], off offset:16
	v_pk_mul_f32 v[136:137], v[68:69], v[120:121]
	global_store_dwordx4 v[138:139], v[120:123], off offset:16
	v_pk_mul_f32 v[178:179], v[70:71], v[122:123]
	v_cvt_pk_bf16_f32 v134, v168, v169
	v_cvt_pk_bf16_f32 v135, v142, v143
	v_cvt_pk_bf16_f32 v136, v136, v137
	s_nop 0
	v_cvt_pk_bf16_f32 v137, v178, v179
	global_store_dwordx4 v[140:141], v[134:137], off
	s_nop 0
	v_mul_f32_e32 v121, v121, v121
	v_mul_f32_e32 v123, v123, v123
	v_fmac_f32_e32 v121, v120, v120
	v_fmac_f32_e32 v123, v122, v122
	v_add_f32_e32 v120, v121, v123
	v_add_f32_e32 v120, v124, v120
	s_waitcnt vmcnt(24)
	v_pk_fma_f32 v[118:119], v[118:119], 0.5, v[226:227] op_sel_hi:[1,0,1]
	v_pk_fma_f32 v[116:117], v[116:117], 0.5, v[224:225] op_sel_hi:[1,0,1]
	global_load_dwordx4 v[224:227], v[208:209], off offset:512
	global_store_dwordx4 v[138:139], v[116:119], off offset:512
	s_nop 0
	v_mul_f32_e32 v121, v117, v117
	v_mul_f32_e32 v122, v119, v119
	v_fmac_f32_e32 v121, v116, v116
	v_fmac_f32_e32 v122, v118, v118
	v_add_f32_e32 v121, v121, v122
	v_add_f32_e32 v120, v120, v121
	v_pk_mul_f32 v[116:117], v[60:61], v[116:117]
	v_pk_mul_f32 v[118:119], v[62:63], v[118:119]
	s_waitcnt vmcnt(25)
	v_pk_fma_f32 v[114:115], v[114:115], 0.5, v[230:231] op_sel_hi:[1,0,1]
	v_pk_fma_f32 v[112:113], v[112:113], 0.5, v[228:229] op_sel_hi:[1,0,1]
	global_load_dwordx4 v[228:231], v[208:209], off offset:528
	v_mul_f32_e32 v122, v115, v115
	v_mul_f32_e32 v121, v113, v113
	v_fmac_f32_e32 v121, v112, v112
	v_fmac_f32_e32 v122, v114, v114
	v_add_f32_e32 v121, v121, v122
	v_add_f32_e32 v124, v120, v121
	ds_bpermute_b32 v125, v132, v124
	global_store_dwordx4 v[138:139], v[112:115], off offset:528
	v_pk_mul_f32 v[122:123], v[56:57], v[112:113]
	v_pk_mul_f32 v[120:121], v[58:59], v[114:115]
	v_cvt_pk_bf16_f32 v114, v116, v117
	s_waitcnt lgkmcnt(0)
	v_add_f32_e32 v112, v124, v125
	ds_bpermute_b32 v113, v133, v112
	v_cvt_pk_bf16_f32 v115, v118, v119
	v_cvt_pk_bf16_f32 v116, v122, v123
	v_cvt_pk_bf16_f32 v117, v120, v121
	global_store_dwordx4 v[140:141], v[114:117], off offset:256
	s_and_saveexec_b64 s[16:17], s[6:7]
	s_cbranch_execz .LBB0_396
	v_lshl_add_u64 v[114:115], v[128:129], 0, s[42:43]
	v_lshl_add_u64 v[114:115], v[114:115], 4, s[20:21]
	s_waitcnt lgkmcnt(0)
	v_add_f32_e32 v112, v112, v113
	global_store_dword v[114:115], v112, off
.LBB0_396:
	s_or_b64 exec, exec, s[16:17]
	s_waitcnt lgkmcnt(0)
	v_or_b32_e32 v112, 32, v164
	v_cmp_lt_i32_e32 vcc, s84, v112
	s_and_saveexec_b64 s[16:17], vcc
	s_xor_b64 s[16:17], exec, s[16:17]
	v_add_u32_e32 v152, 0xffffc020, v164
	v_lshlrev_b64 v[114:115], 12, v[152:153]
	v_lshl_add_u64 v[114:115], s[70:71], 0, v[114:115]
	v_mov_b32_e32 v113, v153
	s_andn2_saveexec_b64 s[16:17], s[16:17]
	v_ashrrev_i32_e32 v113, 31, v112
	v_lshlrev_b64 v[114:115], 12, v[112:113]
	v_lshl_add_u64 v[114:115], s[68:69], 0, v[114:115]
	s_or_b64 exec, exec, s[16:17]
	v_lshl_add_u64 v[118:119], v[114:115], 0, v[166:167]
	v_mov_b32_e32 v254, 0x90000
	v_mov_b32_e32 v255, 0
	v_lshl_add_u64 v[208:209], v[254:255], 0, v[204:205]
	v_lshlrev_b64 v[120:121], 12, v[112:113]
	v_lshl_add_u64 v[120:121], s[22:23], 0, v[120:121]
	v_lshl_add_u64 v[120:121], v[120:121], 0, v[166:167]
	v_lshlrev_b64 v[122:123], 11, v[112:113]
	v_lshl_add_u64 v[122:123], s[72:73], 0, v[122:123]
	v_lshl_add_u64 v[122:123], v[162:163], 1, v[122:123]
	s_waitcnt vmcnt(27)
	v_pk_fma_f32 v[110:111], v[110:111], 0.5, v[234:235] op_sel_hi:[1,0,1]
	v_pk_fma_f32 v[108:109], v[108:109], 0.5, v[232:233] op_sel_hi:[1,0,1]
	global_load_dwordx4 v[232:235], v[208:209], off
	global_store_dwordx4 v[120:121], v[108:111], off
	s_nop 0
	v_pk_mul_f32 v[124:125], v[74:75], v[110:111]
	v_pk_mul_f32 v[126:127], v[72:73], v[108:109]
	v_mul_f32_e32 v109, v109, v109
	v_mul_f32_e32 v111, v111, v111
	v_fmac_f32_e32 v109, v108, v108
	v_fmac_f32_e32 v111, v110, v110
	v_add_f32_e32 v108, v109, v111
	s_waitcnt vmcnt(28)
; __device__ __forceinline__ unsigned cvt_pk_bf16(float lo, float hi) { unsigned r; asm volatile("v_cvt_pk_bf16_f32 %0, %1, %2" : "=v"(r) : "v"(lo), "v"(hi)); return r; }
;     __device__ __forceinline__ void operator()(const f32x4 (&acc)[2][2][4][2], const Unit& u, int wr, int wc, int fr, int fq) const {
;     ...
;             for (int m = 0; m < 4; ++m) {
;                 const int row = row0 + ai * HALF + m * 16;
;                 const float* xr = (row < M_P) ? xin_p + (size_t)row * DM : xin_s + (size_t)(row - M_P) * DM;
;                 float* orow = out + (size_t)row * DM;
;                 float ss = 0.f;
; #pragma unroll
;                 for (int bj = 0; bj < 2; ++bj) {
;                     f32x4 o[2];
; #pragma unroll
;                     for (int n = 0; n < 2; ++n) { const f32x4 xv = *(const f32x4*)(xr + col0 + bj * HALF + 4 * n); o[n] = xv + acc[ai][bj][m][n] * (0.5f * ALPHA2); *(f32x4*)(orow + col0 + bj * HALF + 4 * n) = o[n]; }
;                     if constexpr (WX) {
; #pragma unroll
;                         for (int n = 0; n < 2; ++n) ss += (o[n][0] * o[n][0] + o[n][1] * o[n][1]) + (o[n][2] * o[n][2] + o[n][3] * o[n][3]);
;                         const f32x4 a = o[0] * gv[bj][0], b = o[1] * gv[bj][1];
;                         u32x4 w; w.x = cvt_pk_bf16(a[0], a[1]); w.y = cvt_pk_bf16(a[2], a[3]); w.z = cvt_pk_bf16(b[0], b[1]); w.w = cvt_pk_bf16(b[2], b[3]);
;                         *(u32x4*)(xn + (size_t)row * DM + col0 + bj * HALF) = w;
;                     }
;                 }
;                 if constexpr (WX) { ss += __shfl_xor(ss, 16); ss += __shfl_xor(ss, 32); if (fq == 0) ssq[((size_t)u.pn * MROWS + row) * 4 + wc] = ss; }
	v_pk_fma_f32 v[104:105], v[104:105], 0.5, v[236:237] op_sel_hi:[1,0,1]
	v_pk_fma_f32 v[106:107], v[106:107], 0.5, v[238:239] op_sel_hi:[1,0,1]
	global_load_dwordx4 v[236:239], v[208:209], off offset:16
	v_pk_mul_f32 v[116:117], v[68:69], v[104:105]
	global_store_dwordx4 v[120:121], v[104:107], off offset:16
	v_pk_mul_f32 v[128:129], v[70:71], v[106:107]
	v_cvt_pk_bf16_f32 v114, v126, v127
	v_cvt_pk_bf16_f32 v115, v124, v125
	v_cvt_pk_bf16_f32 v116, v116, v117
	s_nop 0
	v_cvt_pk_bf16_f32 v117, v128, v129
	global_store_dwordx4 v[122:123], v[114:117], off
	s_nop 0
	v_mul_f32_e32 v105, v105, v105
	v_mul_f32_e32 v107, v107, v107
	v_fmac_f32_e32 v105, v104, v104
	v_fmac_f32_e32 v107, v106, v106
	v_add_f32_e32 v104, v105, v107
	v_add_f32_e32 v104, v108, v104
	s_waitcnt vmcnt(30)
	v_pk_fma_f32 v[102:103], v[102:103], 0.5, v[244:245] op_sel_hi:[1,0,1]
	v_pk_fma_f32 v[100:101], v[100:101], 0.5, v[242:243] op_sel_hi:[1,0,1]
	global_load_dwordx4 v[242:245], v[208:209], off offset:512
	global_store_dwordx4 v[120:121], v[100:103], off offset:512
	s_nop 0
	v_mul_f32_e32 v105, v101, v101
	v_mul_f32_e32 v106, v103, v103
	v_fmac_f32_e32 v105, v100, v100
	v_fmac_f32_e32 v106, v102, v102
	v_add_f32_e32 v105, v105, v106
	v_add_f32_e32 v104, v104, v105
	v_pk_mul_f32 v[100:101], v[60:61], v[100:101]
	v_pk_mul_f32 v[102:103], v[62:63], v[102:103]
	s_waitcnt vmcnt(31)
	v_pk_fma_f32 v[98:99], v[98:99], 0.5, v[248:249] op_sel_hi:[1,0,1]
	v_pk_fma_f32 v[96:97], v[96:97], 0.5, v[246:247] op_sel_hi:[1,0,1]
	global_load_dwordx4 v[246:249], v[208:209], off offset:528
	v_mul_f32_e32 v106, v99, v99
	v_mul_f32_e32 v105, v97, v97
	v_fmac_f32_e32 v105, v96, v96
	v_fmac_f32_e32 v106, v98, v98
	v_add_f32_e32 v105, v105, v106
	v_add_f32_e32 v108, v104, v105
	ds_bpermute_b32 v109, v132, v108
	global_store_dwordx4 v[120:121], v[96:99], off offset:528
	v_pk_mul_f32 v[106:107], v[56:57], v[96:97]
	v_pk_mul_f32 v[104:105], v[58:59], v[98:99]
	v_cvt_pk_bf16_f32 v98, v100, v101
	s_waitcnt lgkmcnt(0)
	v_add_f32_e32 v96, v108, v109
	ds_bpermute_b32 v97, v133, v96
	v_cvt_pk_bf16_f32 v99, v102, v103
	v_cvt_pk_bf16_f32 v100, v106, v107
	v_cvt_pk_bf16_f32 v101, v104, v105
	global_store_dwordx4 v[122:123], v[98:101], off offset:256
	s_and_saveexec_b64 s[16:17], s[6:7]
	s_cbranch_execz .LBB0_402
	v_lshl_add_u64 v[98:99], v[112:113], 0, s[42:43]
	v_lshl_add_u64 v[98:99], v[98:99], 4, s[20:21]
	s_waitcnt lgkmcnt(0)
	v_add_f32_e32 v96, v96, v97
	global_store_dword v[98:99], v96, off
.LBB0_402:
	s_or_b64 exec, exec, s[16:17]
	s_waitcnt lgkmcnt(0)
	v_or_b32_e32 v96, 48, v164
	v_cmp_lt_i32_e32 vcc, s84, v96
	s_and_saveexec_b64 s[16:17], vcc
	s_xor_b64 s[16:17], exec, s[16:17]
	v_add_u32_e32 v152, 0xffffc030, v164
	v_lshlrev_b64 v[98:99], 12, v[152:153]
	v_lshl_add_u64 v[98:99], s[70:71], 0, v[98:99]
	v_mov_b32_e32 v97, v153
	s_andn2_saveexec_b64 s[16:17], s[16:17]
	v_ashrrev_i32_e32 v97, 31, v96
	v_lshlrev_b64 v[98:99], 12, v[96:97]
	v_lshl_add_u64 v[98:99], s[68:69], 0, v[98:99]
	s_or_b64 exec, exec, s[16:17]
	v_lshl_add_u64 v[102:103], v[98:99], 0, v[166:167]
	v_mov_b32_e32 v254, 0xa0000
	v_mov_b32_e32 v255, 0
	v_lshl_add_u64 v[208:209], v[254:255], 0, v[204:205]
	v_lshlrev_b64 v[104:105], 12, v[96:97]
	v_lshl_add_u64 v[104:105], s[22:23], 0, v[104:105]
	v_lshl_add_u64 v[104:105], v[104:105], 0, v[166:167]
	v_lshlrev_b64 v[106:107], 11, v[96:97]
	v_lshl_add_u64 v[106:107], s[72:73], 0, v[106:107]
	v_lshl_add_u64 v[106:107], v[162:163], 1, v[106:107]
	s_waitcnt vmcnt(33)
	v_pk_fma_f32 v[94:95], v[94:95], 0.5, v[194:195] op_sel_hi:[1,0,1]
	v_pk_fma_f32 v[92:93], v[92:93], 0.5, v[192:193] op_sel_hi:[1,0,1]
	global_load_dwordx4 v[192:195], v[208:209], off
	global_store_dwordx4 v[104:105], v[92:95], off
	s_nop 0
	v_pk_mul_f32 v[108:109], v[74:75], v[94:95]
	v_pk_mul_f32 v[110:111], v[72:73], v[92:93]
	v_mul_f32_e32 v93, v93, v93
	v_mul_f32_e32 v95, v95, v95
	v_fmac_f32_e32 v93, v92, v92
	v_fmac_f32_e32 v95, v94, v94
	v_add_f32_e32 v92, v93, v95
	s_waitcnt vmcnt(34)
	v_pk_fma_f32 v[88:89], v[88:89], 0.5, v[196:197] op_sel_hi:[1,0,1]
	v_pk_fma_f32 v[90:91], v[90:91], 0.5, v[198:199] op_sel_hi:[1,0,1]
	global_load_dwordx4 v[196:199], v[208:209], off offset:16
	v_pk_mul_f32 v[100:101], v[68:69], v[88:89]
	global_store_dwordx4 v[104:105], v[88:91], off offset:16
	v_pk_mul_f32 v[112:113], v[70:71], v[90:91]
	v_cvt_pk_bf16_f32 v98, v110, v111
	v_cvt_pk_bf16_f32 v99, v108, v109
	v_cvt_pk_bf16_f32 v100, v100, v101
	s_nop 0
	v_cvt_pk_bf16_f32 v101, v112, v113
	global_store_dwordx4 v[106:107], v[98:101], off
	s_nop 0
	v_mul_f32_e32 v89, v89, v89
	v_mul_f32_e32 v91, v91, v91
	v_fmac_f32_e32 v89, v88, v88
	v_fmac_f32_e32 v91, v90, v90
	v_add_f32_e32 v88, v89, v91
	v_add_f32_e32 v88, v92, v88
	s_waitcnt vmcnt(36)
	v_pk_fma_f32 v[86:87], v[86:87], 0.5, v[202:203] op_sel_hi:[1,0,1]
	v_pk_fma_f32 v[84:85], v[84:85], 0.5, v[200:201] op_sel_hi:[1,0,1]
	global_load_dwordx4 v[200:203], v[208:209], off offset:512
	global_store_dwordx4 v[104:105], v[84:87], off offset:512
	s_nop 0
	v_mul_f32_e32 v89, v85, v85
	v_mul_f32_e32 v90, v87, v87
	v_fmac_f32_e32 v89, v84, v84
	v_fmac_f32_e32 v90, v86, v86
	v_add_f32_e32 v89, v89, v90
	v_add_f32_e32 v88, v88, v89
	v_pk_mul_f32 v[84:85], v[60:61], v[84:85]
	v_pk_mul_f32 v[86:87], v[62:63], v[86:87]
	s_waitcnt vmcnt(37)
	v_pk_fma_f32 v[82:83], v[82:83], 0.5, v[214:215] op_sel_hi:[1,0,1]
	v_pk_fma_f32 v[80:81], v[80:81], 0.5, v[212:213] op_sel_hi:[1,0,1]
	global_load_dwordx4 v[212:215], v[208:209], off offset:528
	v_mul_f32_e32 v90, v83, v83
	v_mul_f32_e32 v89, v81, v81
	v_fmac_f32_e32 v89, v80, v80
	v_fmac_f32_e32 v90, v82, v82
	v_add_f32_e32 v89, v89, v90
	v_add_f32_e32 v92, v88, v89
	ds_bpermute_b32 v93, v132, v92
	global_store_dwordx4 v[104:105], v[80:83], off offset:528
	v_pk_mul_f32 v[90:91], v[56:57], v[80:81]
	v_pk_mul_f32 v[88:89], v[58:59], v[82:83]
	v_cvt_pk_bf16_f32 v82, v84, v85
	s_waitcnt lgkmcnt(0)
	v_add_f32_e32 v80, v92, v93
	ds_bpermute_b32 v81, v133, v80
	v_cvt_pk_bf16_f32 v83, v86, v87
	v_cvt_pk_bf16_f32 v84, v90, v91
	v_cvt_pk_bf16_f32 v85, v88, v89
	global_store_dwordx4 v[106:107], v[82:85], off offset:256
	s_and_saveexec_b64 s[16:17], s[6:7]
	s_cbranch_execz .LBB0_408
	v_lshl_add_u64 v[82:83], v[96:97], 0, s[42:43]
	v_lshl_add_u64 v[82:83], v[82:83], 4, s[20:21]
	s_waitcnt lgkmcnt(0)
	v_add_f32_e32 v80, v80, v81
	global_store_dword v[82:83], v80, off
; __device__ __forceinline__ unsigned cvt_pk_bf16(float lo, float hi) { unsigned r; asm volatile("v_cvt_pk_bf16_f32 %0, %1, %2" : "=v"(r) : "v"(lo), "v"(hi)); return r; }
;     __device__ __forceinline__ void operator()(const f32x4 (&acc)[2][2][4][2], const Unit& u, int wr, int wc, int fr, int fq) const {
;     ...
;             for (int m = 0; m < 4; ++m) {
;                 const int row = row0 + ai * HALF + m * 16;
;                 const float* xr = (row < M_P) ? xin_p + (size_t)row * DM : xin_s + (size_t)(row - M_P) * DM;
;                 float* orow = out + (size_t)row * DM;
;                 float ss = 0.f;
; #pragma unroll
;                 for (int bj = 0; bj < 2; ++bj) {
;                     f32x4 o[2];
; #pragma unroll
;                     for (int n = 0; n < 2; ++n) { const f32x4 xv = *(const f32x4*)(xr + col0 + bj * HALF + 4 * n); o[n] = xv + acc[ai][bj][m][n] * (0.5f * ALPHA2); *(f32x4*)(orow + col0 + bj * HALF + 4 * n) = o[n]; }
;                     if constexpr (WX) {
; #pragma unroll
;                         for (int n = 0; n < 2; ++n) ss += (o[n][0] * o[n][0] + o[n][1] * o[n][1]) + (o[n][2] * o[n][2] + o[n][3] * o[n][3]);
;                         const f32x4 a = o[0] * gv[bj][0], b = o[1] * gv[bj][1];
;                         u32x4 w; w.x = cvt_pk_bf16(a[0], a[1]); w.y = cvt_pk_bf16(a[2], a[3]); w.z = cvt_pk_bf16(b[0], b[1]); w.w = cvt_pk_bf16(b[2], b[3]);
;                         *(u32x4*)(xn + (size_t)row * DM + col0 + bj * HALF) = w;
;                     }
;                 }
;                 if constexpr (WX) { ss += __shfl_xor(ss, 16); ss += __shfl_xor(ss, 32); if (fq == 0) ssq[((size_t)u.pn * MROWS + row) * 4 + wc] = ss; }
.LBB0_408:
	s_or_b64 exec, exec, s[16:17]
	s_movk_i32 s16, 0x3f7f
	s_waitcnt lgkmcnt(0)
	v_add_u32_e32 v80, 0x80, v164
	v_cmp_lt_i32_e32 vcc, s16, v164
	s_and_saveexec_b64 s[16:17], vcc
	s_xor_b64 s[16:17], exec, s[16:17]
	v_add_u32_e32 v152, 0xffffc080, v164
	v_lshlrev_b64 v[82:83], 12, v[152:153]
	v_lshl_add_u64 v[82:83], s[70:71], 0, v[82:83]
	v_mov_b32_e32 v81, v153
	s_andn2_saveexec_b64 s[16:17], s[16:17]
	v_ashrrev_i32_e32 v81, 31, v80
	v_lshlrev_b64 v[82:83], 12, v[80:81]
	v_lshl_add_u64 v[82:83], s[68:69], 0, v[82:83]
	s_or_b64 exec, exec, s[16:17]
	v_lshl_add_u64 v[86:87], v[82:83], 0, v[166:167]
	v_mov_b32_e32 v254, 0xb0000
	v_mov_b32_e32 v255, 0
	v_lshl_add_u64 v[208:209], v[254:255], 0, v[204:205]
	v_lshlrev_b64 v[88:89], 12, v[80:81]
	v_lshl_add_u64 v[88:89], s[22:23], 0, v[88:89]
	v_lshl_add_u64 v[88:89], v[88:89], 0, v[166:167]
	v_lshlrev_b64 v[90:91], 11, v[80:81]
	v_lshl_add_u64 v[90:91], s[72:73], 0, v[90:91]
	v_lshl_add_u64 v[90:91], v[162:163], 1, v[90:91]
	s_waitcnt vmcnt(29)
	v_pk_fma_f32 v[78:79], v[78:79], 0.5, v[218:219] op_sel_hi:[1,0,1]
	v_pk_fma_f32 v[76:77], v[76:77], 0.5, v[216:217] op_sel_hi:[1,0,1]
	global_load_dwordx4 v[216:219], v[208:209], off
	global_store_dwordx4 v[88:89], v[76:79], off
	s_nop 0
	v_pk_mul_f32 v[92:93], v[74:75], v[78:79]
	v_pk_mul_f32 v[94:95], v[72:73], v[76:77]
	v_mul_f32_e32 v77, v77, v77
	v_mul_f32_e32 v79, v79, v79
	v_fmac_f32_e32 v77, v76, v76
	v_fmac_f32_e32 v79, v78, v78
	v_add_f32_e32 v76, v77, v79
	s_waitcnt vmcnt(29)
	v_pk_fma_f32 v[64:65], v[64:65], 0.5, v[220:221] op_sel_hi:[1,0,1]
	v_pk_fma_f32 v[66:67], v[66:67], 0.5, v[222:223] op_sel_hi:[1,0,1]
	global_load_dwordx4 v[220:223], v[208:209], off offset:16
	v_pk_mul_f32 v[84:85], v[68:69], v[64:65]
	global_store_dwordx4 v[88:89], v[64:67], off offset:16
	v_pk_mul_f32 v[96:97], v[70:71], v[66:67]
	v_cvt_pk_bf16_f32 v82, v94, v95
	v_cvt_pk_bf16_f32 v83, v92, v93
	v_cvt_pk_bf16_f32 v84, v84, v85
	s_nop 0
	v_cvt_pk_bf16_f32 v85, v96, v97
	global_store_dwordx4 v[90:91], v[82:85], off
	s_nop 0
	v_mul_f32_e32 v65, v65, v65
	v_mul_f32_e32 v67, v67, v67
	v_fmac_f32_e32 v65, v64, v64
	v_fmac_f32_e32 v67, v66, v66
	v_add_f32_e32 v64, v65, v67
	v_add_f32_e32 v64, v76, v64
	s_waitcnt vmcnt(29)
	v_pk_fma_f32 v[54:55], v[54:55], 0.5, v[226:227] op_sel_hi:[1,0,1]
	v_pk_fma_f32 v[52:53], v[52:53], 0.5, v[224:225] op_sel_hi:[1,0,1]
	global_load_dwordx4 v[224:227], v[208:209], off offset:512
	global_store_dwordx4 v[88:89], v[52:55], off offset:512
	s_nop 0
	v_mul_f32_e32 v65, v53, v53
	v_mul_f32_e32 v66, v55, v55
	v_fmac_f32_e32 v65, v52, v52
	v_fmac_f32_e32 v66, v54, v54
	v_add_f32_e32 v65, v65, v66
	v_add_f32_e32 v64, v64, v65
	v_pk_mul_f32 v[52:53], v[60:61], v[52:53]
	v_pk_mul_f32 v[54:55], v[62:63], v[54:55]
	s_waitcnt vmcnt(29)
	v_pk_fma_f32 v[50:51], v[50:51], 0.5, v[230:231] op_sel_hi:[1,0,1]
	v_pk_fma_f32 v[48:49], v[48:49], 0.5, v[228:229] op_sel_hi:[1,0,1]
	global_load_dwordx4 v[228:231], v[208:209], off offset:528
	v_mul_f32_e32 v66, v51, v51
	v_mul_f32_e32 v65, v49, v49
	v_fmac_f32_e32 v65, v48, v48
	v_fmac_f32_e32 v66, v50, v50
	v_add_f32_e32 v65, v65, v66
	v_add_f32_e32 v76, v64, v65
	ds_bpermute_b32 v77, v132, v76
	global_store_dwordx4 v[88:89], v[48:51], off offset:528
	v_pk_mul_f32 v[66:67], v[56:57], v[48:49]
	v_pk_mul_f32 v[64:65], v[58:59], v[50:51]
	v_cvt_pk_bf16_f32 v50, v52, v53
	s_waitcnt lgkmcnt(0)
	v_add_f32_e32 v48, v76, v77
	ds_bpermute_b32 v49, v133, v48
	v_cvt_pk_bf16_f32 v51, v54, v55
	v_cvt_pk_bf16_f32 v52, v66, v67
	v_cvt_pk_bf16_f32 v53, v64, v65
	global_store_dwordx4 v[90:91], v[50:53], off offset:256
	s_and_saveexec_b64 s[16:17], s[6:7]
	s_cbranch_execz .LBB0_414
	v_lshl_add_u64 v[50:51], v[80:81], 0, s[42:43]
	v_lshl_add_u64 v[50:51], v[50:51], 4, s[20:21]
	s_waitcnt lgkmcnt(0)
	v_add_f32_e32 v48, v48, v49
	global_store_dword v[50:51], v48, off
.LBB0_414:
	s_or_b64 exec, exec, s[16:17]
	s_movk_i32 s16, 0x3f6f
	s_waitcnt lgkmcnt(0)
	v_add_u32_e32 v48, 0x90, v164
	v_cmp_lt_i32_e32 vcc, s16, v164
	s_and_saveexec_b64 s[16:17], vcc
	s_xor_b64 s[16:17], exec, s[16:17]
	v_add_u32_e32 v152, 0xffffc090, v164
	v_lshlrev_b64 v[50:51], 12, v[152:153]
	v_lshl_add_u64 v[50:51], s[70:71], 0, v[50:51]
	v_mov_b32_e32 v49, v153
	s_andn2_saveexec_b64 s[16:17], s[16:17]
	v_ashrrev_i32_e32 v49, 31, v48
	v_lshlrev_b64 v[50:51], 12, v[48:49]
	v_lshl_add_u64 v[50:51], s[68:69], 0, v[50:51]
	s_or_b64 exec, exec, s[16:17]
	v_lshl_add_u64 v[54:55], v[50:51], 0, v[166:167]
	s_nop 0
	v_lshlrev_b64 v[64:65], 12, v[48:49]
	v_lshl_add_u64 v[64:65], s[22:23], 0, v[64:65]
	v_lshl_add_u64 v[64:65], v[64:65], 0, v[166:167]
	v_lshlrev_b64 v[66:67], 11, v[48:49]
	v_lshl_add_u64 v[66:67], s[72:73], 0, v[66:67]
	v_lshl_add_u64 v[66:67], v[162:163], 1, v[66:67]
	s_waitcnt vmcnt(29)
	v_pk_fma_f32 v[46:47], v[46:47], 0.5, v[234:235] op_sel_hi:[1,0,1]
	v_pk_fma_f32 v[44:45], v[44:45], 0.5, v[232:233] op_sel_hi:[1,0,1]
	global_store_dwordx4 v[64:65], v[44:47], off
	s_nop 0
	v_pk_mul_f32 v[76:77], v[74:75], v[46:47]
	v_pk_mul_f32 v[78:79], v[72:73], v[44:45]
	v_mul_f32_e32 v45, v45, v45
	v_mul_f32_e32 v47, v47, v47
	v_fmac_f32_e32 v45, v44, v44
	v_fmac_f32_e32 v47, v46, v46
	v_add_f32_e32 v44, v45, v47
	s_waitcnt vmcnt(28)
	v_pk_fma_f32 v[40:41], v[40:41], 0.5, v[236:237] op_sel_hi:[1,0,1]
	v_pk_fma_f32 v[42:43], v[42:43], 0.5, v[238:239] op_sel_hi:[1,0,1]
	v_pk_mul_f32 v[52:53], v[68:69], v[40:41]
	global_store_dwordx4 v[64:65], v[40:43], off offset:16
	v_pk_mul_f32 v[80:81], v[70:71], v[42:43]
	v_cvt_pk_bf16_f32 v50, v78, v79
	v_cvt_pk_bf16_f32 v51, v76, v77
	v_cvt_pk_bf16_f32 v52, v52, v53
	s_nop 0
	v_cvt_pk_bf16_f32 v53, v80, v81
	global_store_dwordx4 v[66:67], v[50:53], off
	s_nop 0
	v_mul_f32_e32 v41, v41, v41
	v_mul_f32_e32 v43, v43, v43
	v_fmac_f32_e32 v41, v40, v40
	v_fmac_f32_e32 v43, v42, v42
	v_add_f32_e32 v40, v41, v43
	v_add_f32_e32 v40, v44, v40
	s_waitcnt vmcnt(27)
; __device__ __forceinline__ unsigned cvt_pk_bf16(float lo, float hi) { unsigned r; asm volatile("v_cvt_pk_bf16_f32 %0, %1, %2" : "=v"(r) : "v"(lo), "v"(hi)); return r; }
;     __device__ __forceinline__ void operator()(const f32x4 (&acc)[2][2][4][2], const Unit& u, int wr, int wc, int fr, int fq) const {
;     ...
;             for (int m = 0; m < 4; ++m) {
;                 const int row = row0 + ai * HALF + m * 16;
;                 const float* xr = (row < M_P) ? xin_p + (size_t)row * DM : xin_s + (size_t)(row - M_P) * DM;
;                 float* orow = out + (size_t)row * DM;
;                 float ss = 0.f;
; #pragma unroll
;                 for (int bj = 0; bj < 2; ++bj) {
;                     f32x4 o[2];
; #pragma unroll
;                     for (int n = 0; n < 2; ++n) { const f32x4 xv = *(const f32x4*)(xr + col0 + bj * HALF + 4 * n); o[n] = xv + acc[ai][bj][m][n] * (0.5f * ALPHA2); *(f32x4*)(orow + col0 + bj * HALF + 4 * n) = o[n]; }
;                     if constexpr (WX) {
; #pragma unroll
;                         for (int n = 0; n < 2; ++n) ss += (o[n][0] * o[n][0] + o[n][1] * o[n][1]) + (o[n][2] * o[n][2] + o[n][3] * o[n][3]);
;                         const f32x4 a = o[0] * gv[bj][0], b = o[1] * gv[bj][1];
;                         u32x4 w; w.x = cvt_pk_bf16(a[0], a[1]); w.y = cvt_pk_bf16(a[2], a[3]); w.z = cvt_pk_bf16(b[0], b[1]); w.w = cvt_pk_bf16(b[2], b[3]);
;                         *(u32x4*)(xn + (size_t)row * DM + col0 + bj * HALF) = w;
;                     }
;                 }
;                 if constexpr (WX) { ss += __shfl_xor(ss, 16); ss += __shfl_xor(ss, 32); if (fq == 0) ssq[((size_t)u.pn * MROWS + row) * 4 + wc] = ss; }
	v_pk_fma_f32 v[38:39], v[38:39], 0.5, v[244:245] op_sel_hi:[1,0,1]
	v_pk_fma_f32 v[36:37], v[36:37], 0.5, v[242:243] op_sel_hi:[1,0,1]
	global_store_dwordx4 v[64:65], v[36:39], off offset:512
	s_nop 0
	v_mul_f32_e32 v41, v37, v37
	v_mul_f32_e32 v42, v39, v39
	v_fmac_f32_e32 v41, v36, v36
	v_fmac_f32_e32 v42, v38, v38
	v_add_f32_e32 v41, v41, v42
	v_add_f32_e32 v40, v40, v41
	v_pk_mul_f32 v[36:37], v[60:61], v[36:37]
	v_pk_mul_f32 v[38:39], v[62:63], v[38:39]
	s_waitcnt vmcnt(26)
	v_pk_fma_f32 v[34:35], v[34:35], 0.5, v[248:249] op_sel_hi:[1,0,1]
	v_pk_fma_f32 v[32:33], v[32:33], 0.5, v[246:247] op_sel_hi:[1,0,1]
	v_mul_f32_e32 v42, v35, v35
	v_mul_f32_e32 v41, v33, v33
	v_fmac_f32_e32 v41, v32, v32
	v_fmac_f32_e32 v42, v34, v34
	v_add_f32_e32 v41, v41, v42
	v_add_f32_e32 v44, v40, v41
	ds_bpermute_b32 v45, v132, v44
	global_store_dwordx4 v[64:65], v[32:35], off offset:528
	v_pk_mul_f32 v[42:43], v[56:57], v[32:33]
	v_pk_mul_f32 v[40:41], v[58:59], v[34:35]
	v_cvt_pk_bf16_f32 v34, v36, v37
	s_waitcnt lgkmcnt(0)
	v_add_f32_e32 v32, v44, v45
	ds_bpermute_b32 v33, v133, v32
	v_cvt_pk_bf16_f32 v35, v38, v39
	v_cvt_pk_bf16_f32 v36, v42, v43
	v_cvt_pk_bf16_f32 v37, v40, v41
	global_store_dwordx4 v[66:67], v[34:37], off offset:256
	s_and_saveexec_b64 s[16:17], s[6:7]
	s_cbranch_execz .LBB0_420
	v_lshl_add_u64 v[34:35], v[48:49], 0, s[42:43]
	v_lshl_add_u64 v[34:35], v[34:35], 4, s[20:21]
	s_waitcnt lgkmcnt(0)
	v_add_f32_e32 v32, v32, v33
	global_store_dword v[34:35], v32, off
.LBB0_420:
	s_or_b64 exec, exec, s[16:17]
	s_waitcnt lgkmcnt(0)
	v_add_u32_e32 v32, 0xa0, v164
	v_cmp_lt_i32_e32 vcc, s85, v164
	s_and_saveexec_b64 s[16:17], vcc
	s_xor_b64 s[16:17], exec, s[16:17]
	v_add_u32_e32 v152, 0xffffc0a0, v164
	v_lshlrev_b64 v[34:35], 12, v[152:153]
	v_lshl_add_u64 v[34:35], s[70:71], 0, v[34:35]
	v_mov_b32_e32 v33, v153
	s_andn2_saveexec_b64 s[16:17], s[16:17]
	v_ashrrev_i32_e32 v33, 31, v32
	v_lshlrev_b64 v[34:35], 12, v[32:33]
	v_lshl_add_u64 v[34:35], s[68:69], 0, v[34:35]
	s_or_b64 exec, exec, s[16:17]
	v_lshl_add_u64 v[38:39], v[34:35], 0, v[166:167]
	s_nop 0
	v_lshlrev_b64 v[40:41], 12, v[32:33]
	v_lshl_add_u64 v[40:41], s[22:23], 0, v[40:41]
	v_lshl_add_u64 v[40:41], v[40:41], 0, v[166:167]
	v_lshlrev_b64 v[42:43], 11, v[32:33]
	v_lshl_add_u64 v[42:43], s[72:73], 0, v[42:43]
	v_lshl_add_u64 v[42:43], v[162:163], 1, v[42:43]
	s_waitcnt vmcnt(25)
	v_pk_fma_f32 v[30:31], v[30:31], 0.5, v[194:195] op_sel_hi:[1,0,1]
	v_pk_fma_f32 v[28:29], v[28:29], 0.5, v[192:193] op_sel_hi:[1,0,1]
	global_store_dwordx4 v[40:41], v[28:31], off
	s_nop 0
	v_pk_mul_f32 v[44:45], v[74:75], v[30:31]
	v_pk_mul_f32 v[46:47], v[72:73], v[28:29]
	v_mul_f32_e32 v29, v29, v29
	v_mul_f32_e32 v31, v31, v31
	v_fmac_f32_e32 v29, v28, v28
	v_fmac_f32_e32 v31, v30, v30
	v_add_f32_e32 v28, v29, v31
	s_waitcnt vmcnt(24)
	v_pk_fma_f32 v[24:25], v[24:25], 0.5, v[196:197] op_sel_hi:[1,0,1]
	v_pk_fma_f32 v[26:27], v[26:27], 0.5, v[198:199] op_sel_hi:[1,0,1]
	v_pk_mul_f32 v[36:37], v[68:69], v[24:25]
	global_store_dwordx4 v[40:41], v[24:27], off offset:16
	v_pk_mul_f32 v[48:49], v[70:71], v[26:27]
	v_cvt_pk_bf16_f32 v34, v46, v47
	v_cvt_pk_bf16_f32 v35, v44, v45
	v_cvt_pk_bf16_f32 v36, v36, v37
	s_nop 0
	v_cvt_pk_bf16_f32 v37, v48, v49
	global_store_dwordx4 v[42:43], v[34:37], off
	s_nop 0
	v_mul_f32_e32 v25, v25, v25
	v_mul_f32_e32 v27, v27, v27
	v_fmac_f32_e32 v25, v24, v24
	v_fmac_f32_e32 v27, v26, v26
	v_add_f32_e32 v24, v25, v27
	v_add_f32_e32 v24, v28, v24
	s_waitcnt vmcnt(23)
	v_pk_fma_f32 v[22:23], v[22:23], 0.5, v[202:203] op_sel_hi:[1,0,1]
	v_pk_fma_f32 v[20:21], v[20:21], 0.5, v[200:201] op_sel_hi:[1,0,1]
	global_store_dwordx4 v[40:41], v[20:23], off offset:512
	s_nop 0
	v_mul_f32_e32 v25, v21, v21
	v_mul_f32_e32 v26, v23, v23
	v_fmac_f32_e32 v25, v20, v20
	v_fmac_f32_e32 v26, v22, v22
	v_add_f32_e32 v25, v25, v26
	v_add_f32_e32 v24, v24, v25
	v_pk_mul_f32 v[20:21], v[60:61], v[20:21]
	v_pk_mul_f32 v[22:23], v[62:63], v[22:23]
	s_waitcnt vmcnt(22)
	v_pk_fma_f32 v[18:19], v[18:19], 0.5, v[214:215] op_sel_hi:[1,0,1]
	v_pk_fma_f32 v[16:17], v[16:17], 0.5, v[212:213] op_sel_hi:[1,0,1]
	v_mul_f32_e32 v26, v19, v19
	v_mul_f32_e32 v25, v17, v17
	v_fmac_f32_e32 v25, v16, v16
	v_fmac_f32_e32 v26, v18, v18
	v_add_f32_e32 v25, v25, v26
	v_add_f32_e32 v28, v24, v25
	ds_bpermute_b32 v29, v132, v28
	global_store_dwordx4 v[40:41], v[16:19], off offset:528
	v_pk_mul_f32 v[26:27], v[56:57], v[16:17]
	v_pk_mul_f32 v[24:25], v[58:59], v[18:19]
	v_cvt_pk_bf16_f32 v18, v20, v21
	s_waitcnt lgkmcnt(0)
	v_add_f32_e32 v16, v28, v29
	ds_bpermute_b32 v17, v133, v16
	v_cvt_pk_bf16_f32 v19, v22, v23
	v_cvt_pk_bf16_f32 v20, v26, v27
	v_cvt_pk_bf16_f32 v21, v24, v25
	global_store_dwordx4 v[42:43], v[18:21], off offset:256
	s_and_saveexec_b64 s[16:17], s[6:7]
	s_cbranch_execz .LBB0_426
	v_lshl_add_u64 v[18:19], v[32:33], 0, s[42:43]
	v_lshl_add_u64 v[18:19], v[18:19], 4, s[20:21]
	s_waitcnt lgkmcnt(0)
	v_add_f32_e32 v16, v16, v17
	global_store_dword v[18:19], v16, off
; __device__ __forceinline__ unsigned cvt_pk_bf16(float lo, float hi) { unsigned r; asm volatile("v_cvt_pk_bf16_f32 %0, %1, %2" : "=v"(r) : "v"(lo), "v"(hi)); return r; }
;     __device__ __forceinline__ void operator()(const f32x4 (&acc)[2][2][4][2], const Unit& u, int wr, int wc, int fr, int fq) const {
;     ...
;             for (int m = 0; m < 4; ++m) {
;                 const int row = row0 + ai * HALF + m * 16;
;                 const float* xr = (row < M_P) ? xin_p + (size_t)row * DM : xin_s + (size_t)(row - M_P) * DM;
;                 float* orow = out + (size_t)row * DM;
;                 float ss = 0.f;
; #pragma unroll
;                 for (int bj = 0; bj < 2; ++bj) {
;                     f32x4 o[2];
; #pragma unroll
;                     for (int n = 0; n < 2; ++n) { const f32x4 xv = *(const f32x4*)(xr + col0 + bj * HALF + 4 * n); o[n] = xv + acc[ai][bj][m][n] * (0.5f * ALPHA2); *(f32x4*)(orow + col0 + bj * HALF + 4 * n) = o[n]; }
;                     if constexpr (WX) {
; #pragma unroll
;                         for (int n = 0; n < 2; ++n) ss += (o[n][0] * o[n][0] + o[n][1] * o[n][1]) + (o[n][2] * o[n][2] + o[n][3] * o[n][3]);
;                         const f32x4 a = o[0] * gv[bj][0], b = o[1] * gv[bj][1];
;                         u32x4 w; w.x = cvt_pk_bf16(a[0], a[1]); w.y = cvt_pk_bf16(a[2], a[3]); w.z = cvt_pk_bf16(b[0], b[1]); w.w = cvt_pk_bf16(b[2], b[3]);
;                         *(u32x4*)(xn + (size_t)row * DM + col0 + bj * HALF) = w;
;                     }
;                 }
;                 if constexpr (WX) { ss += __shfl_xor(ss, 16); ss += __shfl_xor(ss, 32); if (fq == 0) ssq[((size_t)u.pn * MROWS + row) * 4 + wc] = ss; }
.LBB0_426:
	s_or_b64 exec, exec, s[16:17]
	s_waitcnt lgkmcnt(0)
	v_add_u32_e32 v16, 0xb0, v164
	v_cmp_lt_i32_e32 vcc, s86, v164
	s_and_saveexec_b64 s[16:17], vcc
	s_xor_b64 s[16:17], exec, s[16:17]
	v_add_u32_e32 v152, 0xffffc0b0, v164
	v_lshlrev_b64 v[18:19], 12, v[152:153]
	v_lshl_add_u64 v[18:19], s[70:71], 0, v[18:19]
	v_mov_b32_e32 v17, v153
	s_andn2_saveexec_b64 s[16:17], s[16:17]
	v_ashrrev_i32_e32 v17, 31, v16
	v_lshlrev_b64 v[18:19], 12, v[16:17]
	v_lshl_add_u64 v[18:19], s[68:69], 0, v[18:19]
	s_or_b64 exec, exec, s[16:17]
	v_lshl_add_u64 v[22:23], v[18:19], 0, v[166:167]
	s_nop 0
	v_lshlrev_b64 v[24:25], 12, v[16:17]
	v_lshl_add_u64 v[24:25], s[22:23], 0, v[24:25]
	v_lshl_add_u64 v[24:25], v[24:25], 0, v[166:167]
	v_lshlrev_b64 v[26:27], 11, v[16:17]
	v_lshl_add_u64 v[26:27], s[72:73], 0, v[26:27]
	v_lshl_add_u64 v[26:27], v[162:163], 1, v[26:27]
	s_waitcnt vmcnt(21)
	v_pk_fma_f32 v[14:15], v[14:15], 0.5, v[218:219] op_sel_hi:[1,0,1]
	v_pk_fma_f32 v[12:13], v[12:13], 0.5, v[216:217] op_sel_hi:[1,0,1]
	global_store_dwordx4 v[24:25], v[12:15], off
	s_nop 0
	v_pk_mul_f32 v[28:29], v[74:75], v[14:15]
	v_pk_mul_f32 v[30:31], v[72:73], v[12:13]
	v_mul_f32_e32 v13, v13, v13
	v_mul_f32_e32 v15, v15, v15
	v_fmac_f32_e32 v13, v12, v12
	v_fmac_f32_e32 v15, v14, v14
	v_add_f32_e32 v12, v13, v15
	s_waitcnt vmcnt(20)
	v_pk_fma_f32 v[8:9], v[8:9], 0.5, v[220:221] op_sel_hi:[1,0,1]
	v_pk_fma_f32 v[10:11], v[10:11], 0.5, v[222:223] op_sel_hi:[1,0,1]
	v_pk_mul_f32 v[20:21], v[68:69], v[8:9]
	global_store_dwordx4 v[24:25], v[8:11], off offset:16
	v_pk_mul_f32 v[32:33], v[70:71], v[10:11]
	v_cvt_pk_bf16_f32 v18, v30, v31
	v_cvt_pk_bf16_f32 v19, v28, v29
	v_cvt_pk_bf16_f32 v20, v20, v21
	s_nop 0
	v_cvt_pk_bf16_f32 v21, v32, v33
	global_store_dwordx4 v[26:27], v[18:21], off
	s_nop 0
	v_mul_f32_e32 v9, v9, v9
	v_mul_f32_e32 v11, v11, v11
	v_fmac_f32_e32 v9, v8, v8
	v_fmac_f32_e32 v11, v10, v10
	v_add_f32_e32 v8, v9, v11
	v_add_f32_e32 v8, v12, v8
	s_waitcnt vmcnt(19)
	v_pk_fma_f32 v[6:7], v[6:7], 0.5, v[226:227] op_sel_hi:[1,0,1]
	v_pk_fma_f32 v[4:5], v[4:5], 0.5, v[224:225] op_sel_hi:[1,0,1]
	global_store_dwordx4 v[24:25], v[4:7], off offset:512
	s_nop 0
	v_mul_f32_e32 v9, v5, v5
	v_mul_f32_e32 v10, v7, v7
	v_fmac_f32_e32 v9, v4, v4
	v_fmac_f32_e32 v10, v6, v6
	v_add_f32_e32 v9, v9, v10
	v_add_f32_e32 v8, v8, v9
	v_pk_mul_f32 v[4:5], v[60:61], v[4:5]
	v_pk_mul_f32 v[6:7], v[62:63], v[6:7]
	s_waitcnt vmcnt(18)
	v_pk_fma_f32 v[2:3], v[2:3], 0.5, v[230:231] op_sel_hi:[1,0,1]
	v_pk_fma_f32 v[0:1], v[0:1], 0.5, v[228:229] op_sel_hi:[1,0,1]
	v_mul_f32_e32 v10, v3, v3
	v_mul_f32_e32 v9, v1, v1
	v_fmac_f32_e32 v9, v0, v0
	v_fmac_f32_e32 v10, v2, v2
	v_add_f32_e32 v9, v9, v10
	v_add_f32_e32 v12, v8, v9
	ds_bpermute_b32 v13, v132, v12
	global_store_dwordx4 v[24:25], v[0:3], off offset:528
	v_pk_mul_f32 v[10:11], v[56:57], v[0:1]
	v_pk_mul_f32 v[8:9], v[58:59], v[2:3]
	v_cvt_pk_bf16_f32 v2, v4, v5
	s_waitcnt lgkmcnt(0)
	v_add_f32_e32 v0, v12, v13
	ds_bpermute_b32 v1, v133, v0
	v_cvt_pk_bf16_f32 v3, v6, v7
	v_cvt_pk_bf16_f32 v4, v10, v11
	v_cvt_pk_bf16_f32 v5, v8, v9
	global_store_dwordx4 v[26:27], v[2:5], off offset:256
	s_and_saveexec_b64 s[16:17], s[6:7]
	s_cbranch_execz .LBB0_432
	v_lshl_add_u64 v[2:3], v[16:17], 0, s[42:43]
	v_lshl_add_u64 v[2:3], v[2:3], 4, s[20:21]
	s_waitcnt lgkmcnt(0)
	v_add_f32_e32 v0, v0, v1
	global_store_dword v[2:3], v0, off

; __device__ __forceinline__ unsigned cvt_pk_bf16(float lo, float hi) { unsigned r; asm volatile("v_cvt_pk_bf16_f32 %0, %1, %2" : "=v"(r) : "v"(lo), "v"(hi)); return r; }
; __device__ __forceinline__ float sigmoidf_(float v) { return __builtin_amdgcn_rcpf(1.0f + __builtin_amdgcn_exp2f(-1.4426950408889634f * v)); }
; __device__ __forceinline__ float rstd_of(const float* ssq, int row) {
;     const f32x4* p = (const f32x4*)ssq + row; const f32x4 s = (p[0] + p[MROWS]) + (p[2 * MROWS] + p[3 * MROWS]);
;     return 1.0f / sqrtf(((s[0] + s[1]) + (s[2] + s[3])) * (1.0f / 1024.0f) + RMS_EPS); }
;     __device__ __forceinline__ void operator()(const f32x4 (&acc)[2][2][4][2], const Unit& u, int wr, int wc, int fr, int fq) const {
;     ...
;                 const int row = row0 + ai * HALF + m * 16;
;                 const float rs = ssq ? rstd_of(ssq, row) : 1.0f;
;                 float h[8];
; #pragma unroll
;                 for (int n = 0; n < 2; ++n)
; #pragma unroll
;                     for (int e = 0; e < 4; ++e) { const float g = acc[ai][0][m][n][e] * rs, uu = acc[ai][1][m][n][e] * rs; h[n * 4 + e] = g * sigmoidf_(g) * uu; }
;                 u32x4 w; w.x = cvt_pk_bf16(h[0], h[1]); w.y = cvt_pk_bf16(h[2], h[3]); w.z = cvt_pk_bf16(h[4], h[5]); w.w = cvt_pk_bf16(h[6], h[7]);
;                 *(u32x4*)(H + (size_t)row * DFF + colh) = w;
.LBB0_1160:
	v_lshl_add_u32 v144, s8, 8, v149
	v_ashrrev_i32_e32 v145, 31, v144
	v_cndmask_b32_e64 v146, 0, 1, s[84:85]
	v_mov_b32_e32 v148, 1.0
	v_cmp_ne_u32_e64 s[0:1], 1, v146
	s_andn2_b64 vcc, exec, s[84:85]
	v_lshl_add_u64 v[146:147], v[144:145], 4, s[24:25]
	v_mov_b32_e32 v150, 1.0
	s_cbranch_vccnz .LBB0_1162
	v_add_co_u32_e32 v206, vcc, 0xc0000, v146
	s_nop 1
	v_addc_co_u32_e32 v207, vcc, 0, v147, vcc
	v_add_co_u32_e32 v208, vcc, 0x180000, v146
	s_nop 1
	v_addc_co_u32_e32 v209, vcc, 0, v147, vcc
	v_add_co_u32_e32 v250, vcc, 0x240000, v146
	s_nop 1
	v_addc_co_u32_e32 v251, vcc, 0, v147, vcc
	global_load_dwordx4 v[174:177], v[146:147], off
	global_load_dwordx4 v[178:181], v[206:207], off
	global_load_dwordx4 v[182:185], v[208:209], off
	global_load_dwordx4 v[186:189], v[250:251], off
	global_load_dwordx4 v[190:193], v[146:147], off offset:256
	global_load_dwordx4 v[194:197], v[206:207], off offset:256
	global_load_dwordx4 v[198:201], v[208:209], off offset:256
	global_load_dwordx4 v[202:205], v[250:251], off offset:256
	global_load_dwordx4 v[212:215], v[146:147], off offset:512
	global_load_dwordx4 v[216:219], v[206:207], off offset:512
	global_load_dwordx4 v[220:223], v[208:209], off offset:512
	global_load_dwordx4 v[224:227], v[250:251], off offset:512
	s_waitcnt vmcnt(8)
	v_pk_add_f32 v[160:161], v[176:177], v[180:181]
	v_pk_add_f32 v[158:159], v[174:175], v[178:179]
	v_pk_add_f32 v[162:163], v[184:185], v[188:189]
	v_pk_add_f32 v[164:165], v[182:183], v[186:187]
	global_load_dwordx4 v[174:177], v[146:147], off offset:768
	global_load_dwordx4 v[178:181], v[206:207], off offset:768
	global_load_dwordx4 v[182:185], v[208:209], off offset:768
	global_load_dwordx4 v[186:189], v[250:251], off offset:768
	v_pk_add_f32 v[160:161], v[160:161], v[162:163]
	v_pk_add_f32 v[158:159], v[158:159], v[164:165]
	s_nop 0
	v_pk_mov_b32 v[162:163], v[158:159], v[160:161] op_sel:[1,0]
	v_mov_b32_e32 v159, v161
	v_pk_add_f32 v[158:159], v[162:163], v[158:159]
	s_nop 0
	v_add_f32_e32 v145, v158, v159
	v_fmamk_f32 v145, v145, 0x3a800000, v156
	v_mul_f32_e32 v150, 0x4f800000, v145
	v_cmp_gt_f32_e32 vcc, s59, v145
	s_nop 1
	v_cndmask_b32_e32 v145, v145, v150, vcc
	v_sqrt_f32_e32 v150, v145
	s_nop 0
	v_add_u32_e32 v158, -1, v150
	v_add_u32_e32 v159, 1, v150
	v_fma_f32 v160, -v158, v150, v145
	v_fma_f32 v161, -v159, v150, v145
	v_cmp_ge_f32_e64 s[8:9], 0, v160
	s_nop 1
	v_cndmask_b32_e64 v150, v150, v158, s[8:9]
	v_cmp_lt_f32_e64 s[8:9], 0, v161
	s_nop 1
	v_cndmask_b32_e64 v150, v150, v159, s[8:9]
	v_mul_f32_e32 v158, 0x37800000, v150
	v_cndmask_b32_e32 v150, v150, v158, vcc
	v_cmp_class_f32_e32 vcc, v145, v157
	s_nop 1
	v_cndmask_b32_e32 v145, v150, v145, vcc
	v_div_scale_f32 v150, s[8:9], v145, v145, 1.0
	v_rcp_f32_e32 v158, v150
	v_div_scale_f32 v159, vcc, 1.0, v145, 1.0
	v_fma_f32 v160, -v150, v158, 1.0
	v_fmac_f32_e32 v158, v160, v158
	v_mul_f32_e32 v160, v159, v158
	v_fma_f32 v161, -v150, v160, v159
	v_fmac_f32_e32 v160, v161, v158
	v_fma_f32 v150, -v150, v160, v159
	v_div_fmas_f32 v150, v150, v158, v160
	v_div_fixup_f32 v150, v150, v145, 1.0
.LBB0_1162:
	v_mov_b32_e32 v158, v120
	v_mov_b32_e32 v159, v124
	v_pk_mul_f32 v[158:159], v[158:159], v[150:151] op_sel_hi:[1,0]
	v_mov_b32_e32 v124, v121
	v_mul_f32_e32 v120, 0xbfb8aa3b, v159
	v_exp_f32_e32 v145, v120
	v_pk_mul_f32 v[124:125], v[124:125], v[150:151] op_sel_hi:[1,0]
	s_and_b64 vcc, exec, s[0:1]
	v_mul_f32_e32 v120, 0xbfb8aa3b, v125
	v_exp_f32_e32 v121, v120
	v_add_f32_e32 v145, 1.0, v145
	v_rcp_f32_e32 v145, v145
	v_lshl_or_b32 v120, s44, 7, v152
	v_add_f32_e32 v121, 1.0, v121
	v_rcp_f32_e32 v160, v121
	v_mul_f32_e32 v145, v159, v145
	v_mul_f32_e32 v145, v158, v145
	v_mov_b32_e32 v158, v122
	v_mov_b32_e32 v159, v126
	v_pk_mul_f32 v[158:159], v[158:159], v[150:151] op_sel_hi:[1,0]
	v_mov_b32_e32 v126, v123
	v_mul_f32_e32 v122, 0xbfb8aa3b, v159
	v_mul_f32_e32 v125, v125, v160
	v_exp_f32_e32 v160, v122
	v_pk_mul_f32 v[122:123], v[126:127], v[150:151] op_sel_hi:[1,0]
	v_mul_f32_e32 v127, v124, v125
	v_mul_f32_e32 v126, 0xbfb8aa3b, v123
	v_exp_f32_e32 v126, v126
	v_add_f32_e32 v124, 1.0, v160
	v_rcp_f32_e32 v160, v124
	v_mov_b32_e32 v125, v116
	v_add_f32_e32 v124, 1.0, v126
	v_rcp_f32_e32 v126, v124
	v_mov_b32_e32 v124, v112
	v_pk_mul_f32 v[124:125], v[124:125], v[150:151] op_sel_hi:[1,0]
	v_mul_f32_e32 v116, v159, v160
	v_mul_f32_e32 v112, 0xbfb8aa3b, v125
	v_exp_f32_e32 v112, v112
	v_mul_f32_e32 v158, v158, v116
	v_mov_b32_e32 v116, v113
	v_mul_f32_e32 v123, v123, v126
	v_add_f32_e32 v112, 1.0, v112
	v_rcp_f32_e32 v126, v112
	v_pk_mul_f32 v[112:113], v[116:117], v[150:151] op_sel_hi:[1,0]
	v_mul_f32_e32 v122, v122, v123
	v_mul_f32_e32 v116, 0xbfb8aa3b, v113
	v_exp_f32_e32 v116, v116
	v_mul_f32_e32 v117, v125, v126
	v_mul_f32_e32 v123, v124, v117
	v_mov_b32_e32 v117, v118
	v_add_f32_e32 v116, 1.0, v116
	v_rcp_f32_e32 v124, v116
	v_mov_b32_e32 v116, v114
	v_pk_mul_f32 v[116:117], v[116:117], v[150:151] op_sel_hi:[1,0]
	v_mov_b32_e32 v118, v115
	v_mul_f32_e32 v114, 0xbfb8aa3b, v117
	v_exp_f32_e32 v125, v114
	v_pk_mul_f32 v[114:115], v[118:119], v[150:151] op_sel_hi:[1,0]
	v_mul_f32_e32 v113, v113, v124
	v_mul_f32_e32 v118, 0xbfb8aa3b, v115
	v_exp_f32_e32 v118, v118
	v_add_f32_e32 v119, 1.0, v125
	v_rcp_f32_e32 v119, v119
	v_mul_f32_e32 v124, v112, v113
	v_add_f32_e32 v118, 1.0, v118
	v_rcp_f32_e32 v118, v118
	v_mul_f32_e32 v112, v117, v119
	v_mul_f32_e32 v116, v116, v112
	v_ashrrev_i32_e32 v121, 31, v120
	v_mul_f32_e32 v112, v115, v118
	v_mul_f32_e32 v115, v114, v112
	v_cvt_pk_bf16_f32 v112, v145, v127
	v_cvt_pk_bf16_f32 v113, v158, v122
	v_cvt_pk_bf16_f32 v114, v123, v124
	v_cvt_pk_bf16_f32 v115, v116, v115
	v_mov_b64_e32 v[116:117], s[30:31]
	v_mad_i64_i32 v[116:117], s[8:9], v144, s60, v[116:117]
	v_lshl_add_u64 v[116:117], v[120:121], 1, v[116:117]
	global_store_dwordx4 v[116:117], v[112:115], off
	s_cbranch_vccnz .LBB0_1164
; __device__ __forceinline__ unsigned cvt_pk_bf16(float lo, float hi) { unsigned r; asm volatile("v_cvt_pk_bf16_f32 %0, %1, %2" : "=v"(r) : "v"(lo), "v"(hi)); return r; }
; __device__ __forceinline__ float sigmoidf_(float v) { return __builtin_amdgcn_rcpf(1.0f + __builtin_amdgcn_exp2f(-1.4426950408889634f * v)); }
; __device__ __forceinline__ float rstd_of(const float* ssq, int row) {
;     const f32x4* p = (const f32x4*)ssq + row; const f32x4 s = (p[0] + p[MROWS]) + (p[2 * MROWS] + p[3 * MROWS]);
;     return 1.0f / sqrtf(((s[0] + s[1]) + (s[2] + s[3])) * (1.0f / 1024.0f) + RMS_EPS); }
;     __device__ __forceinline__ void operator()(const f32x4 (&acc)[2][2][4][2], const Unit& u, int wr, int wc, int fr, int fq) const {
;     ...
;                 const int row = row0 + ai * HALF + m * 16;
;                 const float rs = ssq ? rstd_of(ssq, row) : 1.0f;
;                 float h[8];
; #pragma unroll
;                 for (int n = 0; n < 2; ++n)
; #pragma unroll
;                     for (int e = 0; e < 4; ++e) { const float g = acc[ai][0][m][n][e] * rs, uu = acc[ai][1][m][n][e] * rs; h[n * 4 + e] = g * sigmoidf_(g) * uu; }
;                 u32x4 w; w.x = cvt_pk_bf16(h[0], h[1]); w.y = cvt_pk_bf16(h[2], h[3]); w.z = cvt_pk_bf16(h[4], h[5]); w.w = cvt_pk_bf16(h[6], h[7]);
;                 *(u32x4*)(H + (size_t)row * DFF + colh) = w;
	s_waitcnt vmcnt(9)
	v_pk_add_f32 v[114:115], v[192:193], v[196:197]
	v_pk_add_f32 v[112:113], v[190:191], v[194:195]
	v_pk_add_f32 v[116:117], v[200:201], v[204:205]
	v_pk_add_f32 v[118:119], v[198:199], v[202:203]
	global_load_dwordx4 v[190:193], v[146:147], off offset:2048
	global_load_dwordx4 v[194:197], v[206:207], off offset:2048
	global_load_dwordx4 v[198:201], v[208:209], off offset:2048
	global_load_dwordx4 v[202:205], v[250:251], off offset:2048
	v_pk_add_f32 v[114:115], v[114:115], v[116:117]
	v_pk_add_f32 v[112:113], v[112:113], v[118:119]
	s_nop 0
	v_pk_mov_b32 v[116:117], v[112:113], v[114:115] op_sel:[1,0]
	v_mov_b32_e32 v113, v115
	v_pk_add_f32 v[112:113], v[116:117], v[112:113]
	s_nop 0
	v_add_f32_e32 v112, v112, v113
	v_fmamk_f32 v112, v112, 0x3a800000, v156
	v_mul_f32_e32 v113, 0x4f800000, v112
	v_cmp_gt_f32_e32 vcc, s59, v112
	s_nop 1
	v_cndmask_b32_e32 v112, v112, v113, vcc
	v_sqrt_f32_e32 v113, v112
	s_nop 0
	v_add_u32_e32 v114, -1, v113
	v_add_u32_e32 v115, 1, v113
	v_fma_f32 v116, -v114, v113, v112
	v_fma_f32 v117, -v115, v113, v112
	v_cmp_ge_f32_e64 s[8:9], 0, v116
	s_nop 1
	v_cndmask_b32_e64 v113, v113, v114, s[8:9]
	v_cmp_lt_f32_e64 s[8:9], 0, v117
	s_nop 1
	v_cndmask_b32_e64 v113, v113, v115, s[8:9]
	v_mul_f32_e32 v114, 0x37800000, v113
	v_cndmask_b32_e32 v113, v113, v114, vcc
	v_cmp_class_f32_e32 vcc, v112, v157
	s_nop 1
	v_cndmask_b32_e32 v112, v113, v112, vcc
	v_div_scale_f32 v113, s[8:9], v112, v112, 1.0
	v_rcp_f32_e32 v114, v113
	v_div_scale_f32 v115, vcc, 1.0, v112, 1.0
	v_fma_f32 v116, -v113, v114, 1.0
	v_fmac_f32_e32 v114, v116, v114
	v_mul_f32_e32 v116, v115, v114
	v_fma_f32 v117, -v113, v116, v115
	v_fmac_f32_e32 v116, v117, v114
	v_fma_f32 v113, -v113, v116, v115
	v_div_fmas_f32 v113, v113, v114, v116
	v_div_fixup_f32 v148, v113, v112, 1.0
.LBB0_1164:
	s_nop 0
	v_mov_b32_e32 v112, v104
	v_mov_b32_e32 v113, v108
	v_pk_mul_f32 v[112:113], v[112:113], v[148:149] op_sel_hi:[1,0]
	v_mov_b32_e32 v108, v105
	v_mul_f32_e32 v104, 0xbfb8aa3b, v113
	v_exp_f32_e32 v104, v104
	v_pk_mul_f32 v[108:109], v[108:109], v[148:149] op_sel_hi:[1,0]
	v_or_b32_e32 v114, 16, v144
	v_mul_f32_e32 v105, 0xbfb8aa3b, v109
	v_exp_f32_e32 v105, v105
	v_add_f32_e32 v104, 1.0, v104
	v_rcp_f32_e32 v115, v104
	s_and_b64 vcc, exec, s[0:1]
	v_add_f32_e32 v104, 1.0, v105
	v_rcp_f32_e32 v105, v104
	v_mul_f32_e32 v113, v113, v115
	v_mul_f32_e32 v115, v112, v113
	v_mov_b32_e32 v112, v106
	v_mov_b32_e32 v113, v110
	v_pk_mul_f32 v[112:113], v[112:113], v[148:149] op_sel_hi:[1,0]
	v_mov_b32_e32 v110, v107
	v_mul_f32_e32 v106, 0xbfb8aa3b, v113
	v_mul_f32_e32 v105, v109, v105
	v_exp_f32_e32 v109, v106
	v_pk_mul_f32 v[106:107], v[110:111], v[148:149] op_sel_hi:[1,0]
	v_mul_f32_e32 v105, v108, v105
	v_mul_f32_e32 v110, 0xbfb8aa3b, v107
	v_exp_f32_e32 v110, v110
	v_add_f32_e32 v108, 1.0, v109
	v_rcp_f32_e32 v111, v108
	v_mov_b32_e32 v109, v100
	v_add_f32_e32 v108, 1.0, v110
	v_rcp_f32_e32 v110, v108
	v_mov_b32_e32 v108, v96
	v_pk_mul_f32 v[108:109], v[108:109], v[148:149] op_sel_hi:[1,0]
	v_mul_f32_e32 v100, v113, v111
	v_mul_f32_e32 v96, 0xbfb8aa3b, v109
	v_exp_f32_e32 v96, v96
	v_mul_f32_e32 v111, v112, v100
	v_mov_b32_e32 v100, v97
	v_mul_f32_e32 v107, v107, v110
	v_add_f32_e32 v96, 1.0, v96
	v_rcp_f32_e32 v110, v96
	v_pk_mul_f32 v[96:97], v[100:101], v[148:149] op_sel_hi:[1,0]
	v_mul_f32_e32 v106, v106, v107
	v_mul_f32_e32 v100, 0xbfb8aa3b, v97
	v_exp_f32_e32 v100, v100
	v_mul_f32_e32 v101, v109, v110
	v_mul_f32_e32 v107, v108, v101
	v_mov_b32_e32 v101, v102
	v_add_f32_e32 v100, 1.0, v100
	v_rcp_f32_e32 v108, v100
	v_mov_b32_e32 v100, v98
	v_pk_mul_f32 v[100:101], v[100:101], v[148:149] op_sel_hi:[1,0]
	v_mov_b32_e32 v102, v99
	v_mul_f32_e32 v98, 0xbfb8aa3b, v101
	v_exp_f32_e32 v109, v98
	v_pk_mul_f32 v[98:99], v[102:103], v[148:149] op_sel_hi:[1,0]
	v_mul_f32_e32 v97, v97, v108
	v_mul_f32_e32 v102, 0xbfb8aa3b, v99
	v_exp_f32_e32 v102, v102
	v_add_f32_e32 v103, 1.0, v109
	v_rcp_f32_e32 v103, v103
	v_mul_f32_e32 v108, v96, v97
	v_add_f32_e32 v102, 1.0, v102
	v_rcp_f32_e32 v102, v102
	v_mul_f32_e32 v96, v101, v103
	v_mul_f32_e32 v100, v100, v96
	v_mov_b32_e32 v104, 1.0
	v_mul_f32_e32 v96, v99, v102
	v_mul_f32_e32 v99, v98, v96
	v_cvt_pk_bf16_f32 v96, v115, v105
	v_cvt_pk_bf16_f32 v97, v111, v106
	v_cvt_pk_bf16_f32 v98, v107, v108
	v_cvt_pk_bf16_f32 v99, v100, v99
	v_mov_b64_e32 v[100:101], s[30:31]
	v_mad_i64_i32 v[100:101], s[8:9], v114, s60, v[100:101]
	v_lshl_add_u64 v[100:101], v[120:121], 1, v[100:101]
	global_store_dwordx4 v[100:101], v[96:99], off
	s_nop 1
	v_mov_b32_e32 v96, 1.0
	s_cbranch_vccnz .LBB0_1166
	s_waitcnt vmcnt(10)
	v_pk_add_f32 v[98:99], v[214:215], v[218:219]
	v_pk_add_f32 v[96:97], v[212:213], v[216:217]
	v_pk_add_f32 v[100:101], v[222:223], v[226:227]
	v_pk_add_f32 v[102:103], v[220:221], v[224:225]
	global_load_dwordx4 v[212:215], v[146:147], off offset:2304
	global_load_dwordx4 v[216:219], v[206:207], off offset:2304
	global_load_dwordx4 v[220:223], v[208:209], off offset:2304
	global_load_dwordx4 v[224:227], v[250:251], off offset:2304
	v_pk_add_f32 v[98:99], v[98:99], v[100:101]
	v_pk_add_f32 v[96:97], v[96:97], v[102:103]
	s_nop 0
	v_pk_mov_b32 v[100:101], v[96:97], v[98:99] op_sel:[1,0]
	v_mov_b32_e32 v97, v99
	v_pk_add_f32 v[96:97], v[100:101], v[96:97]
	s_nop 0
	v_add_f32_e32 v96, v96, v97
	v_fmamk_f32 v96, v96, 0x3a800000, v156
	v_mul_f32_e32 v97, 0x4f800000, v96
	v_cmp_gt_f32_e32 vcc, s59, v96
	s_nop 1
	v_cndmask_b32_e32 v96, v96, v97, vcc
	v_sqrt_f32_e32 v97, v96
	s_nop 0
	v_add_u32_e32 v98, -1, v97
	v_add_u32_e32 v99, 1, v97
	v_fma_f32 v100, -v98, v97, v96
	v_fma_f32 v101, -v99, v97, v96
	v_cmp_ge_f32_e64 s[8:9], 0, v100
	s_nop 1
	v_cndmask_b32_e64 v97, v97, v98, s[8:9]
	v_cmp_lt_f32_e64 s[8:9], 0, v101
	s_nop 1
	v_cndmask_b32_e64 v97, v97, v99, s[8:9]
	v_mul_f32_e32 v98, 0x37800000, v97
	v_cndmask_b32_e32 v97, v97, v98, vcc
	v_cmp_class_f32_e32 vcc, v96, v157
	s_nop 1
	v_cndmask_b32_e32 v96, v97, v96, vcc
	v_div_scale_f32 v97, s[8:9], v96, v96, 1.0
	v_rcp_f32_e32 v98, v97
	v_div_scale_f32 v99, vcc, 1.0, v96, 1.0
	v_fma_f32 v100, -v97, v98, 1.0
	v_fmac_f32_e32 v98, v100, v98
	v_mul_f32_e32 v100, v99, v98
	v_fma_f32 v101, -v97, v100, v99
	v_fmac_f32_e32 v100, v101, v98
	v_fma_f32 v97, -v97, v100, v99
	v_div_fmas_f32 v97, v97, v98, v100
	v_div_fixup_f32 v96, v97, v96, 1.0
; __device__ __forceinline__ unsigned cvt_pk_bf16(float lo, float hi) { unsigned r; asm volatile("v_cvt_pk_bf16_f32 %0, %1, %2" : "=v"(r) : "v"(lo), "v"(hi)); return r; }
; __device__ __forceinline__ float sigmoidf_(float v) { return __builtin_amdgcn_rcpf(1.0f + __builtin_amdgcn_exp2f(-1.4426950408889634f * v)); }
; __device__ __forceinline__ float rstd_of(const float* ssq, int row) {
;     const f32x4* p = (const f32x4*)ssq + row; const f32x4 s = (p[0] + p[MROWS]) + (p[2 * MROWS] + p[3 * MROWS]);
;     return 1.0f / sqrtf(((s[0] + s[1]) + (s[2] + s[3])) * (1.0f / 1024.0f) + RMS_EPS); }
;     __device__ __forceinline__ void operator()(const f32x4 (&acc)[2][2][4][2], const Unit& u, int wr, int wc, int fr, int fq) const {
;     ...
;                 const int row = row0 + ai * HALF + m * 16;
;                 const float rs = ssq ? rstd_of(ssq, row) : 1.0f;
;                 float h[8];
; #pragma unroll
;                 for (int n = 0; n < 2; ++n)
; #pragma unroll
;                     for (int e = 0; e < 4; ++e) { const float g = acc[ai][0][m][n][e] * rs, uu = acc[ai][1][m][n][e] * rs; h[n * 4 + e] = g * sigmoidf_(g) * uu; }
;                 u32x4 w; w.x = cvt_pk_bf16(h[0], h[1]); w.y = cvt_pk_bf16(h[2], h[3]); w.z = cvt_pk_bf16(h[4], h[5]); w.w = cvt_pk_bf16(h[6], h[7]);
;                 *(u32x4*)(H + (size_t)row * DFF + colh) = w;
.LBB0_1166:
	v_mov_b32_e32 v98, v88
	v_mov_b32_e32 v99, v92
	v_pk_mul_f32 v[98:99], v[98:99], v[96:97] op_sel_hi:[1,0]
	v_mov_b32_e32 v92, v89
	v_mul_f32_e32 v88, 0xbfb8aa3b, v99
	v_exp_f32_e32 v97, v88
	s_and_b64 vcc, exec, s[0:1]
	v_pk_mul_f32 v[88:89], v[92:93], v[96:97] op_sel_hi:[1,0]
	s_nop 0
	v_mul_f32_e32 v92, 0xbfb8aa3b, v89
	v_exp_f32_e32 v92, v92
	v_add_f32_e32 v93, 1.0, v97
	v_rcp_f32_e32 v93, v93
	v_or_b32_e32 v97, 32, v144
	v_add_f32_e32 v92, 1.0, v92
	v_rcp_f32_e32 v92, v92
	v_mul_f32_e32 v93, v99, v93
	v_mul_f32_e32 v98, v98, v93
	v_mov_b32_e32 v93, v94
	v_mul_f32_e32 v89, v89, v92
	v_mov_b32_e32 v92, v90
	v_pk_mul_f32 v[92:93], v[92:93], v[96:97] op_sel_hi:[1,0]
	v_mov_b32_e32 v94, v91
	v_mul_f32_e32 v90, 0xbfb8aa3b, v93
	v_exp_f32_e32 v99, v90
	v_pk_mul_f32 v[90:91], v[94:95], v[96:97] op_sel_hi:[1,0]
	v_mul_f32_e32 v95, v88, v89
	v_mul_f32_e32 v94, 0xbfb8aa3b, v91
	v_exp_f32_e32 v94, v94
	v_add_f32_e32 v88, 1.0, v99
	v_rcp_f32_e32 v99, v88
	v_mov_b32_e32 v89, v84
	v_add_f32_e32 v88, 1.0, v94
	v_rcp_f32_e32 v94, v88
	v_mov_b32_e32 v88, v80
	v_pk_mul_f32 v[88:89], v[88:89], v[96:97] op_sel_hi:[1,0]
	v_mul_f32_e32 v84, v93, v99
	v_mul_f32_e32 v80, 0xbfb8aa3b, v89
	v_exp_f32_e32 v80, v80
	v_mul_f32_e32 v92, v92, v84
	v_mov_b32_e32 v84, v81
	v_mul_f32_e32 v91, v91, v94
	v_add_f32_e32 v80, 1.0, v80
	v_rcp_f32_e32 v93, v80
	v_pk_mul_f32 v[80:81], v[84:85], v[96:97] op_sel_hi:[1,0]
	v_mul_f32_e32 v90, v90, v91
	v_mul_f32_e32 v84, 0xbfb8aa3b, v81
	v_exp_f32_e32 v84, v84
	v_mul_f32_e32 v85, v89, v93
	v_mul_f32_e32 v88, v88, v85
	v_mov_b32_e32 v85, v86
	v_add_f32_e32 v84, 1.0, v84
	v_rcp_f32_e32 v89, v84
	v_mov_b32_e32 v84, v82
	v_pk_mul_f32 v[84:85], v[84:85], v[96:97] op_sel_hi:[1,0]
	v_mov_b32_e32 v86, v83
	v_mul_f32_e32 v82, 0xbfb8aa3b, v85
	v_exp_f32_e32 v91, v82
	v_pk_mul_f32 v[82:83], v[86:87], v[96:97] op_sel_hi:[1,0]
	v_mul_f32_e32 v81, v81, v89
	v_mul_f32_e32 v86, 0xbfb8aa3b, v83
	v_exp_f32_e32 v86, v86
	v_add_f32_e32 v87, 1.0, v91
	v_rcp_f32_e32 v87, v87
	v_mul_f32_e32 v89, v80, v81
	v_add_f32_e32 v86, 1.0, v86
	v_rcp_f32_e32 v86, v86
	v_mul_f32_e32 v80, v85, v87
	v_mul_f32_e32 v84, v84, v80
	v_mul_f32_e32 v80, v83, v86
	v_mul_f32_e32 v83, v82, v80
	v_cvt_pk_bf16_f32 v80, v98, v95
	v_cvt_pk_bf16_f32 v81, v92, v90
	v_cvt_pk_bf16_f32 v82, v88, v89
	v_cvt_pk_bf16_f32 v83, v84, v83
	v_mov_b64_e32 v[84:85], s[30:31]
	v_mad_i64_i32 v[84:85], s[8:9], v97, s60, v[84:85]
	v_lshl_add_u64 v[84:85], v[120:121], 1, v[84:85]
	global_store_dwordx4 v[84:85], v[80:83], off
	s_cbranch_vccnz .LBB0_1168
	s_waitcnt vmcnt(11)
	v_pk_add_f32 v[82:83], v[176:177], v[180:181]
	v_pk_add_f32 v[80:81], v[174:175], v[178:179]
	v_pk_add_f32 v[84:85], v[184:185], v[188:189]
	v_pk_add_f32 v[86:87], v[182:183], v[186:187]
	global_load_dwordx4 v[174:177], v[146:147], off offset:2560
	global_load_dwordx4 v[178:181], v[206:207], off offset:2560
	global_load_dwordx4 v[182:185], v[208:209], off offset:2560
	global_load_dwordx4 v[186:189], v[250:251], off offset:2560
	v_pk_add_f32 v[82:83], v[82:83], v[84:85]
	v_pk_add_f32 v[80:81], v[80:81], v[86:87]
	s_nop 0
	v_pk_mov_b32 v[84:85], v[80:81], v[82:83] op_sel:[1,0]
	v_mov_b32_e32 v81, v83
	v_pk_add_f32 v[80:81], v[84:85], v[80:81]
	s_nop 0
	v_add_f32_e32 v80, v80, v81
	v_fmamk_f32 v80, v80, 0x3a800000, v156
	v_mul_f32_e32 v81, 0x4f800000, v80
	v_cmp_gt_f32_e32 vcc, s59, v80
	s_nop 1
	v_cndmask_b32_e32 v80, v80, v81, vcc
	v_sqrt_f32_e32 v81, v80
	s_nop 0
	v_add_u32_e32 v82, -1, v81
	v_add_u32_e32 v83, 1, v81
	v_fma_f32 v84, -v82, v81, v80
	v_fma_f32 v85, -v83, v81, v80
	v_cmp_ge_f32_e64 s[8:9], 0, v84
	s_nop 1
	v_cndmask_b32_e64 v81, v81, v82, s[8:9]
	v_cmp_lt_f32_e64 s[8:9], 0, v85
	s_nop 1
	v_cndmask_b32_e64 v81, v81, v83, s[8:9]
	v_mul_f32_e32 v82, 0x37800000, v81
	v_cndmask_b32_e32 v81, v81, v82, vcc
	v_cmp_class_f32_e32 vcc, v80, v157
	s_nop 1
	v_cndmask_b32_e32 v80, v81, v80, vcc
	v_div_scale_f32 v81, s[8:9], v80, v80, 1.0
	v_rcp_f32_e32 v82, v81
	v_div_scale_f32 v83, vcc, 1.0, v80, 1.0
	v_fma_f32 v84, -v81, v82, 1.0
	v_fmac_f32_e32 v82, v84, v82
	v_mul_f32_e32 v84, v83, v82
	v_fma_f32 v85, -v81, v84, v83
	v_fmac_f32_e32 v84, v85, v82
	v_fma_f32 v81, -v81, v84, v83
	v_div_fmas_f32 v81, v81, v82, v84
	v_div_fixup_f32 v104, v81, v80, 1.0
; __device__ __forceinline__ unsigned cvt_pk_bf16(float lo, float hi) { unsigned r; asm volatile("v_cvt_pk_bf16_f32 %0, %1, %2" : "=v"(r) : "v"(lo), "v"(hi)); return r; }
; __device__ __forceinline__ float sigmoidf_(float v) { return __builtin_amdgcn_rcpf(1.0f + __builtin_amdgcn_exp2f(-1.4426950408889634f * v)); }
; __device__ __forceinline__ float rstd_of(const float* ssq, int row) {
;     const f32x4* p = (const f32x4*)ssq + row; const f32x4 s = (p[0] + p[MROWS]) + (p[2 * MROWS] + p[3 * MROWS]);
;     return 1.0f / sqrtf(((s[0] + s[1]) + (s[2] + s[3])) * (1.0f / 1024.0f) + RMS_EPS); }
;     __device__ __forceinline__ void operator()(const f32x4 (&acc)[2][2][4][2], const Unit& u, int wr, int wc, int fr, int fq) const {
;     ...
;                 const int row = row0 + ai * HALF + m * 16;
;                 const float rs = ssq ? rstd_of(ssq, row) : 1.0f;
;                 float h[8];
; #pragma unroll
;                 for (int n = 0; n < 2; ++n)
; #pragma unroll
;                     for (int e = 0; e < 4; ++e) { const float g = acc[ai][0][m][n][e] * rs, uu = acc[ai][1][m][n][e] * rs; h[n * 4 + e] = g * sigmoidf_(g) * uu; }
;                 u32x4 w; w.x = cvt_pk_bf16(h[0], h[1]); w.y = cvt_pk_bf16(h[2], h[3]); w.z = cvt_pk_bf16(h[4], h[5]); w.w = cvt_pk_bf16(h[6], h[7]);
;                 *(u32x4*)(H + (size_t)row * DFF + colh) = w;
.LBB0_1168:
	s_nop 0
	v_mov_b32_e32 v80, v72
	v_mov_b32_e32 v81, v76
	v_pk_mul_f32 v[80:81], v[80:81], v[104:105] op_sel_hi:[1,0]
	v_mov_b32_e32 v76, v73
	v_mul_f32_e32 v72, 0xbfb8aa3b, v81
	v_exp_f32_e32 v72, v72
	v_pk_mul_f32 v[76:77], v[76:77], v[104:105] op_sel_hi:[1,0]
	v_or_b32_e32 v82, 48, v144
	v_mul_f32_e32 v73, 0xbfb8aa3b, v77
	v_exp_f32_e32 v73, v73
	v_add_f32_e32 v72, 1.0, v72
	v_rcp_f32_e32 v83, v72
	s_and_b64 vcc, exec, s[0:1]
	v_add_f32_e32 v72, 1.0, v73
	v_rcp_f32_e32 v73, v72
	v_mul_f32_e32 v81, v81, v83
	v_mul_f32_e32 v83, v80, v81
	v_mov_b32_e32 v80, v74
	v_mov_b32_e32 v81, v78
	v_pk_mul_f32 v[80:81], v[80:81], v[104:105] op_sel_hi:[1,0]
	v_mov_b32_e32 v78, v75
	v_mul_f32_e32 v74, 0xbfb8aa3b, v81
	v_mul_f32_e32 v73, v77, v73
	v_exp_f32_e32 v77, v74
	v_pk_mul_f32 v[74:75], v[78:79], v[104:105] op_sel_hi:[1,0]
	v_mul_f32_e32 v73, v76, v73
	v_mul_f32_e32 v78, 0xbfb8aa3b, v75
	v_exp_f32_e32 v78, v78
	v_add_f32_e32 v76, 1.0, v77
	v_rcp_f32_e32 v79, v76
	v_mov_b32_e32 v77, v68
	v_add_f32_e32 v76, 1.0, v78
	v_rcp_f32_e32 v78, v76
	v_mov_b32_e32 v76, v64
	v_pk_mul_f32 v[76:77], v[76:77], v[104:105] op_sel_hi:[1,0]
	v_mul_f32_e32 v68, v81, v79
	v_mul_f32_e32 v64, 0xbfb8aa3b, v77
	v_exp_f32_e32 v64, v64
	v_mul_f32_e32 v79, v80, v68
	v_mov_b32_e32 v68, v65
	v_mul_f32_e32 v75, v75, v78
	v_add_f32_e32 v64, 1.0, v64
	v_rcp_f32_e32 v78, v64
	v_pk_mul_f32 v[64:65], v[68:69], v[104:105] op_sel_hi:[1,0]
	v_mul_f32_e32 v74, v74, v75
	v_mul_f32_e32 v68, 0xbfb8aa3b, v65
	v_exp_f32_e32 v68, v68
	v_mul_f32_e32 v69, v77, v78
	v_mul_f32_e32 v75, v76, v69
	v_mov_b32_e32 v69, v70
	v_add_f32_e32 v68, 1.0, v68
	v_rcp_f32_e32 v76, v68
	v_mov_b32_e32 v68, v66
	v_pk_mul_f32 v[68:69], v[68:69], v[104:105] op_sel_hi:[1,0]
	v_mov_b32_e32 v70, v67
	v_mul_f32_e32 v66, 0xbfb8aa3b, v69
	v_exp_f32_e32 v77, v66
	v_pk_mul_f32 v[66:67], v[70:71], v[104:105] op_sel_hi:[1,0]
	v_mul_f32_e32 v65, v65, v76
	v_mul_f32_e32 v70, 0xbfb8aa3b, v67
	v_exp_f32_e32 v70, v70
	v_add_f32_e32 v71, 1.0, v77
	v_rcp_f32_e32 v71, v71
	v_mul_f32_e32 v76, v64, v65
	v_add_f32_e32 v70, 1.0, v70
	v_rcp_f32_e32 v70, v70
	v_mul_f32_e32 v64, v69, v71
	v_mul_f32_e32 v68, v68, v64
	v_mov_b32_e32 v72, 1.0
	v_mul_f32_e32 v64, v67, v70
	v_mul_f32_e32 v67, v66, v64
	v_cvt_pk_bf16_f32 v64, v83, v73
	v_cvt_pk_bf16_f32 v65, v79, v74
	v_cvt_pk_bf16_f32 v66, v75, v76
	v_cvt_pk_bf16_f32 v67, v68, v67
	v_mov_b64_e32 v[68:69], s[30:31]
	v_mad_i64_i32 v[68:69], s[8:9], v82, s60, v[68:69]
	v_lshl_add_u64 v[68:69], v[120:121], 1, v[68:69]
	global_store_dwordx4 v[68:69], v[64:67], off
	s_nop 1
	v_mov_b32_e32 v64, 1.0
	s_cbranch_vccnz .LBB0_1170
	s_waitcnt vmcnt(11)
	v_pk_add_f32 v[66:67], v[192:193], v[196:197]
	v_pk_add_f32 v[64:65], v[190:191], v[194:195]
	v_pk_add_f32 v[68:69], v[200:201], v[204:205]
	v_pk_add_f32 v[70:71], v[198:199], v[202:203]
	global_load_dwordx4 v[190:193], v[146:147], off offset:2816
	global_load_dwordx4 v[194:197], v[206:207], off offset:2816
	global_load_dwordx4 v[198:201], v[208:209], off offset:2816
	global_load_dwordx4 v[202:205], v[250:251], off offset:2816
	v_pk_add_f32 v[66:67], v[66:67], v[68:69]
	v_pk_add_f32 v[64:65], v[64:65], v[70:71]
	s_nop 0
	v_pk_mov_b32 v[68:69], v[64:65], v[66:67] op_sel:[1,0]
	v_mov_b32_e32 v65, v67
	v_pk_add_f32 v[64:65], v[68:69], v[64:65]
	s_nop 0
	v_add_f32_e32 v64, v64, v65
	v_fmamk_f32 v64, v64, 0x3a800000, v156
	v_mul_f32_e32 v65, 0x4f800000, v64
	v_cmp_gt_f32_e32 vcc, s59, v64
	s_nop 1
	v_cndmask_b32_e32 v64, v64, v65, vcc
	v_sqrt_f32_e32 v65, v64
	s_nop 0
	v_add_u32_e32 v66, -1, v65
	v_add_u32_e32 v67, 1, v65
	v_fma_f32 v68, -v66, v65, v64
	v_fma_f32 v69, -v67, v65, v64
	v_cmp_ge_f32_e64 s[8:9], 0, v68
	s_nop 1
	v_cndmask_b32_e64 v65, v65, v66, s[8:9]
	v_cmp_lt_f32_e64 s[8:9], 0, v69
	s_nop 1
	v_cndmask_b32_e64 v65, v65, v67, s[8:9]
	v_mul_f32_e32 v66, 0x37800000, v65
	v_cndmask_b32_e32 v65, v65, v66, vcc
	v_cmp_class_f32_e32 vcc, v64, v157
	s_nop 1
	v_cndmask_b32_e32 v64, v65, v64, vcc
	v_div_scale_f32 v65, s[8:9], v64, v64, 1.0
	v_rcp_f32_e32 v66, v65
	v_div_scale_f32 v67, vcc, 1.0, v64, 1.0
	v_fma_f32 v68, -v65, v66, 1.0
	v_fmac_f32_e32 v66, v68, v66
	v_mul_f32_e32 v68, v67, v66
	v_fma_f32 v69, -v65, v68, v67
	v_fmac_f32_e32 v68, v69, v66
	v_fma_f32 v65, -v65, v68, v67
	v_div_fmas_f32 v65, v65, v66, v68
	v_div_fixup_f32 v64, v65, v64, 1.0
; __device__ __forceinline__ unsigned cvt_pk_bf16(float lo, float hi) { unsigned r; asm volatile("v_cvt_pk_bf16_f32 %0, %1, %2" : "=v"(r) : "v"(lo), "v"(hi)); return r; }
; __device__ __forceinline__ float sigmoidf_(float v) { return __builtin_amdgcn_rcpf(1.0f + __builtin_amdgcn_exp2f(-1.4426950408889634f * v)); }
; __device__ __forceinline__ float rstd_of(const float* ssq, int row) {
;     const f32x4* p = (const f32x4*)ssq + row; const f32x4 s = (p[0] + p[MROWS]) + (p[2 * MROWS] + p[3 * MROWS]);
;     return 1.0f / sqrtf(((s[0] + s[1]) + (s[2] + s[3])) * (1.0f / 1024.0f) + RMS_EPS); }
;     __device__ __forceinline__ void operator()(const f32x4 (&acc)[2][2][4][2], const Unit& u, int wr, int wc, int fr, int fq) const {
;     ...
;                 const int row = row0 + ai * HALF + m * 16;
;                 const float rs = ssq ? rstd_of(ssq, row) : 1.0f;
;                 float h[8];
; #pragma unroll
;                 for (int n = 0; n < 2; ++n)
; #pragma unroll
;                     for (int e = 0; e < 4; ++e) { const float g = acc[ai][0][m][n][e] * rs, uu = acc[ai][1][m][n][e] * rs; h[n * 4 + e] = g * sigmoidf_(g) * uu; }
;                 u32x4 w; w.x = cvt_pk_bf16(h[0], h[1]); w.y = cvt_pk_bf16(h[2], h[3]); w.z = cvt_pk_bf16(h[4], h[5]); w.w = cvt_pk_bf16(h[6], h[7]);
;                 *(u32x4*)(H + (size_t)row * DFF + colh) = w;
.LBB0_1170:
	v_mov_b32_e32 v66, v56
	v_mov_b32_e32 v67, v60
	v_pk_mul_f32 v[66:67], v[66:67], v[64:65] op_sel_hi:[1,0]
	v_mov_b32_e32 v60, v57
	v_mul_f32_e32 v56, 0xbfb8aa3b, v67
	v_exp_f32_e32 v65, v56
	s_and_b64 vcc, exec, s[0:1]
	v_pk_mul_f32 v[56:57], v[60:61], v[64:65] op_sel_hi:[1,0]
	s_nop 0
	v_mul_f32_e32 v60, 0xbfb8aa3b, v57
	v_exp_f32_e32 v60, v60
	v_add_f32_e32 v61, 1.0, v65
	v_rcp_f32_e32 v61, v61
	v_add_u32_e32 v65, 0x80, v144
	v_add_f32_e32 v60, 1.0, v60
	v_rcp_f32_e32 v60, v60
	v_mul_f32_e32 v61, v67, v61
	v_mul_f32_e32 v66, v66, v61
	v_mov_b32_e32 v61, v62
	v_mul_f32_e32 v57, v57, v60
	v_mov_b32_e32 v60, v58
	v_pk_mul_f32 v[60:61], v[60:61], v[64:65] op_sel_hi:[1,0]
	v_mov_b32_e32 v62, v59
	v_mul_f32_e32 v58, 0xbfb8aa3b, v61
	v_exp_f32_e32 v67, v58
	v_pk_mul_f32 v[58:59], v[62:63], v[64:65] op_sel_hi:[1,0]
	v_mul_f32_e32 v63, v56, v57
	v_mul_f32_e32 v62, 0xbfb8aa3b, v59
	v_exp_f32_e32 v62, v62
	v_add_f32_e32 v56, 1.0, v67
	v_rcp_f32_e32 v67, v56
	v_mov_b32_e32 v57, v52
	v_add_f32_e32 v56, 1.0, v62
	v_rcp_f32_e32 v62, v56
	v_mov_b32_e32 v56, v48
	v_pk_mul_f32 v[56:57], v[56:57], v[64:65] op_sel_hi:[1,0]
	v_mul_f32_e32 v52, v61, v67
	v_mul_f32_e32 v48, 0xbfb8aa3b, v57
	v_exp_f32_e32 v48, v48
	v_mul_f32_e32 v60, v60, v52
	v_mov_b32_e32 v52, v49
	v_mul_f32_e32 v59, v59, v62
	v_add_f32_e32 v48, 1.0, v48
	v_rcp_f32_e32 v61, v48
	v_pk_mul_f32 v[48:49], v[52:53], v[64:65] op_sel_hi:[1,0]
	v_mul_f32_e32 v58, v58, v59
	v_mul_f32_e32 v52, 0xbfb8aa3b, v49
	v_exp_f32_e32 v52, v52
	v_mul_f32_e32 v53, v57, v61
	v_mul_f32_e32 v56, v56, v53
	v_mov_b32_e32 v53, v54
	v_add_f32_e32 v52, 1.0, v52
	v_rcp_f32_e32 v57, v52
	v_mov_b32_e32 v52, v50
	v_pk_mul_f32 v[52:53], v[52:53], v[64:65] op_sel_hi:[1,0]
	v_mov_b32_e32 v54, v51
	v_mul_f32_e32 v50, 0xbfb8aa3b, v53
	v_exp_f32_e32 v59, v50
	v_pk_mul_f32 v[50:51], v[54:55], v[64:65] op_sel_hi:[1,0]
	v_mul_f32_e32 v49, v49, v57
	v_mul_f32_e32 v54, 0xbfb8aa3b, v51
	v_exp_f32_e32 v54, v54
	v_add_f32_e32 v55, 1.0, v59
	v_rcp_f32_e32 v55, v55
	v_mul_f32_e32 v57, v48, v49
	v_add_f32_e32 v54, 1.0, v54
	v_rcp_f32_e32 v54, v54
	v_mul_f32_e32 v48, v53, v55
	v_mul_f32_e32 v52, v52, v48
	v_mul_f32_e32 v48, v51, v54
	v_mul_f32_e32 v51, v50, v48
	v_cvt_pk_bf16_f32 v48, v66, v63
	v_cvt_pk_bf16_f32 v49, v60, v58
	v_cvt_pk_bf16_f32 v50, v56, v57
	v_cvt_pk_bf16_f32 v51, v52, v51
	v_mov_b64_e32 v[52:53], s[30:31]
	v_mad_i64_i32 v[52:53], s[8:9], v65, s60, v[52:53]
	v_lshl_add_u64 v[52:53], v[120:121], 1, v[52:53]
	global_store_dwordx4 v[52:53], v[48:51], off
	s_cbranch_vccnz .LBB0_1172
	s_waitcnt vmcnt(11)
	v_pk_add_f32 v[50:51], v[214:215], v[218:219]
	v_pk_add_f32 v[48:49], v[212:213], v[216:217]
	v_pk_add_f32 v[52:53], v[222:223], v[226:227]
	v_pk_add_f32 v[54:55], v[220:221], v[224:225]
	v_pk_add_f32 v[50:51], v[50:51], v[52:53]
	v_pk_add_f32 v[48:49], v[48:49], v[54:55]
	s_nop 0
	v_pk_mov_b32 v[52:53], v[48:49], v[50:51] op_sel:[1,0]
	v_mov_b32_e32 v49, v51
	v_pk_add_f32 v[48:49], v[52:53], v[48:49]
	s_nop 0
	v_add_f32_e32 v48, v48, v49
	v_fmamk_f32 v48, v48, 0x3a800000, v156
	v_mul_f32_e32 v49, 0x4f800000, v48
	v_cmp_gt_f32_e32 vcc, s59, v48
	s_nop 1
	v_cndmask_b32_e32 v48, v48, v49, vcc
	v_sqrt_f32_e32 v49, v48
	s_nop 0
	v_add_u32_e32 v50, -1, v49
	v_add_u32_e32 v51, 1, v49
	v_fma_f32 v52, -v50, v49, v48
	v_fma_f32 v53, -v51, v49, v48
	v_cmp_ge_f32_e64 s[8:9], 0, v52
	s_nop 1
	v_cndmask_b32_e64 v49, v49, v50, s[8:9]
	v_cmp_lt_f32_e64 s[8:9], 0, v53
	s_nop 1
	v_cndmask_b32_e64 v49, v49, v51, s[8:9]
	v_mul_f32_e32 v50, 0x37800000, v49
	v_cndmask_b32_e32 v49, v49, v50, vcc
	v_cmp_class_f32_e32 vcc, v48, v157
	s_nop 1
	v_cndmask_b32_e32 v48, v49, v48, vcc
	v_div_scale_f32 v49, s[8:9], v48, v48, 1.0
	v_rcp_f32_e32 v50, v49
	v_div_scale_f32 v51, vcc, 1.0, v48, 1.0
	v_fma_f32 v52, -v49, v50, 1.0
	v_fmac_f32_e32 v50, v52, v50
	v_mul_f32_e32 v52, v51, v50
	v_fma_f32 v53, -v49, v52, v51
	v_fmac_f32_e32 v52, v53, v50
	v_fma_f32 v49, -v49, v52, v51
	v_div_fmas_f32 v49, v49, v50, v52
	v_div_fixup_f32 v72, v49, v48, 1.0
.LBB0_1172:
	s_nop 0
	v_mov_b32_e32 v48, v40
	v_mov_b32_e32 v49, v44
	v_pk_mul_f32 v[48:49], v[48:49], v[72:73] op_sel_hi:[1,0]
	v_mov_b32_e32 v44, v41
	v_mul_f32_e32 v40, 0xbfb8aa3b, v49
	v_exp_f32_e32 v40, v40
	v_pk_mul_f32 v[44:45], v[44:45], v[72:73] op_sel_hi:[1,0]
	v_add_u32_e32 v50, 0x90, v144
	v_mul_f32_e32 v41, 0xbfb8aa3b, v45
	v_exp_f32_e32 v41, v41
	v_add_f32_e32 v40, 1.0, v40
	v_rcp_f32_e32 v51, v40
	s_and_b64 vcc, exec, s[0:1]
	v_add_f32_e32 v40, 1.0, v41
	v_rcp_f32_e32 v41, v40
	v_mul_f32_e32 v49, v49, v51
	v_mul_f32_e32 v51, v48, v49
	v_mov_b32_e32 v48, v42
	v_mov_b32_e32 v49, v46
	v_pk_mul_f32 v[48:49], v[48:49], v[72:73] op_sel_hi:[1,0]
	v_mov_b32_e32 v46, v43
	v_mul_f32_e32 v42, 0xbfb8aa3b, v49
	v_mul_f32_e32 v41, v45, v41
	v_exp_f32_e32 v45, v42
	v_pk_mul_f32 v[42:43], v[46:47], v[72:73] op_sel_hi:[1,0]
	v_mul_f32_e32 v41, v44, v41
	v_mul_f32_e32 v46, 0xbfb8aa3b, v43
	v_exp_f32_e32 v46, v46
	v_add_f32_e32 v44, 1.0, v45
	v_rcp_f32_e32 v47, v44
	v_mov_b32_e32 v45, v36
	v_add_f32_e32 v44, 1.0, v46
	v_rcp_f32_e32 v46, v44
	v_mov_b32_e32 v44, v32
	v_pk_mul_f32 v[44:45], v[44:45], v[72:73] op_sel_hi:[1,0]
	v_mul_f32_e32 v36, v49, v47
	v_mul_f32_e32 v32, 0xbfb8aa3b, v45
	v_exp_f32_e32 v32, v32
	v_mul_f32_e32 v47, v48, v36
	v_mov_b32_e32 v36, v33
	v_mul_f32_e32 v43, v43, v46
	v_add_f32_e32 v32, 1.0, v32
	v_rcp_f32_e32 v46, v32
	v_pk_mul_f32 v[32:33], v[36:37], v[72:73] op_sel_hi:[1,0]
	v_mul_f32_e32 v42, v42, v43
	v_mul_f32_e32 v36, 0xbfb8aa3b, v33
	v_exp_f32_e32 v36, v36
	v_mul_f32_e32 v37, v45, v46
	v_mul_f32_e32 v43, v44, v37
	v_mov_b32_e32 v37, v38
	v_add_f32_e32 v36, 1.0, v36
	v_rcp_f32_e32 v44, v36
	v_mov_b32_e32 v36, v34
	v_pk_mul_f32 v[36:37], v[36:37], v[72:73] op_sel_hi:[1,0]
	v_mov_b32_e32 v38, v35
	v_mul_f32_e32 v34, 0xbfb8aa3b, v37
	v_exp_f32_e32 v45, v34
	v_pk_mul_f32 v[34:35], v[38:39], v[72:73] op_sel_hi:[1,0]
	v_mul_f32_e32 v33, v33, v44
	v_mul_f32_e32 v38, 0xbfb8aa3b, v35
	v_exp_f32_e32 v38, v38
	v_add_f32_e32 v39, 1.0, v45
	v_rcp_f32_e32 v39, v39
	v_mul_f32_e32 v44, v32, v33
	v_add_f32_e32 v38, 1.0, v38
	v_rcp_f32_e32 v38, v38
	v_mul_f32_e32 v32, v37, v39
	v_mul_f32_e32 v36, v36, v32
	v_mov_b32_e32 v40, 1.0
	v_mul_f32_e32 v32, v35, v38
	v_mul_f32_e32 v35, v34, v32
	v_cvt_pk_bf16_f32 v32, v51, v41
	v_cvt_pk_bf16_f32 v33, v47, v42
	v_cvt_pk_bf16_f32 v34, v43, v44
	v_cvt_pk_bf16_f32 v35, v36, v35
	v_mov_b64_e32 v[36:37], s[30:31]
	v_mad_i64_i32 v[36:37], s[8:9], v50, s60, v[36:37]
	v_lshl_add_u64 v[36:37], v[120:121], 1, v[36:37]
	global_store_dwordx4 v[36:37], v[32:35], off
	s_nop 1
	v_mov_b32_e32 v32, 1.0
	s_cbranch_vccnz .LBB0_1174
; __device__ __forceinline__ unsigned cvt_pk_bf16(float lo, float hi) { unsigned r; asm volatile("v_cvt_pk_bf16_f32 %0, %1, %2" : "=v"(r) : "v"(lo), "v"(hi)); return r; }
; __device__ __forceinline__ float sigmoidf_(float v) { return __builtin_amdgcn_rcpf(1.0f + __builtin_amdgcn_exp2f(-1.4426950408889634f * v)); }
; __device__ __forceinline__ float rstd_of(const float* ssq, int row) {
;     const f32x4* p = (const f32x4*)ssq + row; const f32x4 s = (p[0] + p[MROWS]) + (p[2 * MROWS] + p[3 * MROWS]);
;     return 1.0f / sqrtf(((s[0] + s[1]) + (s[2] + s[3])) * (1.0f / 1024.0f) + RMS_EPS); }
;     __device__ __forceinline__ void operator()(const f32x4 (&acc)[2][2][4][2], const Unit& u, int wr, int wc, int fr, int fq) const {
;     ...
;                 const int row = row0 + ai * HALF + m * 16;
;                 const float rs = ssq ? rstd_of(ssq, row) : 1.0f;
;                 float h[8];
; #pragma unroll
;                 for (int n = 0; n < 2; ++n)
; #pragma unroll
;                     for (int e = 0; e < 4; ++e) { const float g = acc[ai][0][m][n][e] * rs, uu = acc[ai][1][m][n][e] * rs; h[n * 4 + e] = g * sigmoidf_(g) * uu; }
;                 u32x4 w; w.x = cvt_pk_bf16(h[0], h[1]); w.y = cvt_pk_bf16(h[2], h[3]); w.z = cvt_pk_bf16(h[4], h[5]); w.w = cvt_pk_bf16(h[6], h[7]);
;                 *(u32x4*)(H + (size_t)row * DFF + colh) = w;
	s_waitcnt vmcnt(7)
	v_pk_add_f32 v[34:35], v[176:177], v[180:181]
	v_pk_add_f32 v[32:33], v[174:175], v[178:179]
	v_pk_add_f32 v[36:37], v[184:185], v[188:189]
	v_pk_add_f32 v[38:39], v[182:183], v[186:187]
	v_pk_add_f32 v[34:35], v[34:35], v[36:37]
	v_pk_add_f32 v[32:33], v[32:33], v[38:39]
	s_nop 0
	v_pk_mov_b32 v[36:37], v[32:33], v[34:35] op_sel:[1,0]
	v_mov_b32_e32 v33, v35
	v_pk_add_f32 v[32:33], v[36:37], v[32:33]
	s_nop 0
	v_add_f32_e32 v32, v32, v33
	v_fmamk_f32 v32, v32, 0x3a800000, v156
	v_mul_f32_e32 v33, 0x4f800000, v32
	v_cmp_gt_f32_e32 vcc, s59, v32
	s_nop 1
	v_cndmask_b32_e32 v32, v32, v33, vcc
	v_sqrt_f32_e32 v33, v32
	s_nop 0
	v_add_u32_e32 v34, -1, v33
	v_add_u32_e32 v35, 1, v33
	v_fma_f32 v36, -v34, v33, v32
	v_fma_f32 v37, -v35, v33, v32
	v_cmp_ge_f32_e64 s[8:9], 0, v36
	s_nop 1
	v_cndmask_b32_e64 v33, v33, v34, s[8:9]
	v_cmp_lt_f32_e64 s[8:9], 0, v37
	s_nop 1
	v_cndmask_b32_e64 v33, v33, v35, s[8:9]
	v_mul_f32_e32 v34, 0x37800000, v33
	v_cndmask_b32_e32 v33, v33, v34, vcc
	v_cmp_class_f32_e32 vcc, v32, v157
	s_nop 1
	v_cndmask_b32_e32 v32, v33, v32, vcc
	v_div_scale_f32 v33, s[8:9], v32, v32, 1.0
	v_rcp_f32_e32 v34, v33
	v_div_scale_f32 v35, vcc, 1.0, v32, 1.0
	v_fma_f32 v36, -v33, v34, 1.0
	v_fmac_f32_e32 v34, v36, v34
	v_mul_f32_e32 v36, v35, v34
	v_fma_f32 v37, -v33, v36, v35
	v_fmac_f32_e32 v36, v37, v34
	v_fma_f32 v33, -v33, v36, v35
	v_div_fmas_f32 v33, v33, v34, v36
	v_div_fixup_f32 v32, v33, v32, 1.0
.LBB0_1174:
	v_mov_b32_e32 v34, v24
	v_mov_b32_e32 v35, v28
	v_pk_mul_f32 v[34:35], v[34:35], v[32:33] op_sel_hi:[1,0]
	v_mov_b32_e32 v28, v25
	v_mul_f32_e32 v24, 0xbfb8aa3b, v35
	v_exp_f32_e32 v33, v24
	s_and_b64 vcc, exec, s[0:1]
	v_pk_mul_f32 v[24:25], v[28:29], v[32:33] op_sel_hi:[1,0]
	s_nop 0
	v_mul_f32_e32 v28, 0xbfb8aa3b, v25
	v_exp_f32_e32 v28, v28
	v_add_f32_e32 v29, 1.0, v33
	v_rcp_f32_e32 v29, v29
	v_add_u32_e32 v33, 0xa0, v144
	v_add_f32_e32 v28, 1.0, v28
	v_rcp_f32_e32 v28, v28
	v_mul_f32_e32 v29, v35, v29
	v_mul_f32_e32 v34, v34, v29
	v_mov_b32_e32 v29, v30
	v_mul_f32_e32 v25, v25, v28
	v_mov_b32_e32 v28, v26
	v_pk_mul_f32 v[28:29], v[28:29], v[32:33] op_sel_hi:[1,0]
	v_mov_b32_e32 v30, v27
	v_mul_f32_e32 v26, 0xbfb8aa3b, v29
	v_exp_f32_e32 v35, v26
	v_pk_mul_f32 v[26:27], v[30:31], v[32:33] op_sel_hi:[1,0]
	v_mul_f32_e32 v31, v24, v25
	v_mul_f32_e32 v30, 0xbfb8aa3b, v27
	v_exp_f32_e32 v30, v30
	v_add_f32_e32 v24, 1.0, v35
	v_rcp_f32_e32 v35, v24
	v_mov_b32_e32 v25, v20
	v_add_f32_e32 v24, 1.0, v30
	v_rcp_f32_e32 v30, v24
	v_mov_b32_e32 v24, v16
	v_pk_mul_f32 v[24:25], v[24:25], v[32:33] op_sel_hi:[1,0]
	v_mul_f32_e32 v20, v29, v35
	v_mul_f32_e32 v16, 0xbfb8aa3b, v25
	v_exp_f32_e32 v16, v16
	v_mul_f32_e32 v28, v28, v20
	v_mov_b32_e32 v20, v17
	v_mul_f32_e32 v27, v27, v30
	v_add_f32_e32 v16, 1.0, v16
	v_rcp_f32_e32 v29, v16
	v_pk_mul_f32 v[16:17], v[20:21], v[32:33] op_sel_hi:[1,0]
	v_mul_f32_e32 v26, v26, v27
	v_mul_f32_e32 v20, 0xbfb8aa3b, v17
	v_exp_f32_e32 v20, v20
	v_mul_f32_e32 v21, v25, v29
	v_mul_f32_e32 v24, v24, v21
	v_mov_b32_e32 v21, v22
	v_add_f32_e32 v20, 1.0, v20
	v_rcp_f32_e32 v25, v20
	v_mov_b32_e32 v20, v18
	v_pk_mul_f32 v[20:21], v[20:21], v[32:33] op_sel_hi:[1,0]
	v_mov_b32_e32 v22, v19
	v_mul_f32_e32 v18, 0xbfb8aa3b, v21
	v_exp_f32_e32 v27, v18
	v_pk_mul_f32 v[18:19], v[22:23], v[32:33] op_sel_hi:[1,0]
	v_mul_f32_e32 v17, v17, v25
	v_mul_f32_e32 v22, 0xbfb8aa3b, v19
	v_exp_f32_e32 v22, v22
	v_add_f32_e32 v23, 1.0, v27
	v_rcp_f32_e32 v23, v23
	v_mul_f32_e32 v25, v16, v17
	v_add_f32_e32 v22, 1.0, v22
	v_rcp_f32_e32 v22, v22
	v_mul_f32_e32 v16, v21, v23
	v_mul_f32_e32 v20, v20, v16
	v_mul_f32_e32 v16, v19, v22
	v_mul_f32_e32 v19, v18, v16
	v_cvt_pk_bf16_f32 v16, v34, v31
	v_cvt_pk_bf16_f32 v17, v28, v26
	v_cvt_pk_bf16_f32 v18, v24, v25
	v_cvt_pk_bf16_f32 v19, v20, v19
	v_mov_b64_e32 v[20:21], s[30:31]
	v_mad_i64_i32 v[20:21], s[8:9], v33, s60, v[20:21]
	v_lshl_add_u64 v[20:21], v[120:121], 1, v[20:21]
	global_store_dwordx4 v[20:21], v[16:19], off
	s_cbranch_vccnz .LBB0_1176
	s_waitcnt vmcnt(3)
	v_pk_add_f32 v[18:19], v[192:193], v[196:197]
	v_pk_add_f32 v[16:17], v[190:191], v[194:195]
	v_pk_add_f32 v[20:21], v[200:201], v[204:205]
	v_pk_add_f32 v[22:23], v[198:199], v[202:203]
	v_pk_add_f32 v[18:19], v[18:19], v[20:21]
	v_pk_add_f32 v[16:17], v[16:17], v[22:23]
	s_nop 0
	v_pk_mov_b32 v[20:21], v[16:17], v[18:19] op_sel:[1,0]
	v_mov_b32_e32 v17, v19
	v_pk_add_f32 v[16:17], v[20:21], v[16:17]
	s_nop 0
	v_add_f32_e32 v16, v16, v17
	v_fmamk_f32 v16, v16, 0x3a800000, v156
	v_mul_f32_e32 v17, 0x4f800000, v16
	v_cmp_gt_f32_e32 vcc, s59, v16
	s_nop 1
	v_cndmask_b32_e32 v16, v16, v17, vcc
	v_sqrt_f32_e32 v17, v16
	s_nop 0
	v_add_u32_e32 v18, -1, v17
	v_add_u32_e32 v19, 1, v17
	v_fma_f32 v20, -v18, v17, v16
	v_fma_f32 v21, -v19, v17, v16
	v_cmp_ge_f32_e64 s[0:1], 0, v20
	s_nop 1
	v_cndmask_b32_e64 v17, v17, v18, s[0:1]
	v_cmp_lt_f32_e64 s[0:1], 0, v21
	s_nop 1
	v_cndmask_b32_e64 v17, v17, v19, s[0:1]
	v_mul_f32_e32 v18, 0x37800000, v17
	v_cndmask_b32_e32 v17, v17, v18, vcc
	v_cmp_class_f32_e32 vcc, v16, v157
	s_nop 1
	v_cndmask_b32_e32 v16, v17, v16, vcc
	v_div_scale_f32 v17, s[0:1], v16, v16, 1.0
	v_rcp_f32_e32 v18, v17
	v_div_scale_f32 v19, vcc, 1.0, v16, 1.0
	v_fma_f32 v20, -v17, v18, 1.0
	v_fmac_f32_e32 v18, v20, v18
	v_mul_f32_e32 v20, v19, v18
	v_fma_f32 v21, -v17, v20, v19
	v_fmac_f32_e32 v20, v21, v18
	v_fma_f32 v17, -v17, v20, v19
	v_div_fmas_f32 v17, v17, v18, v20
	v_div_fixup_f32 v40, v17, v16, 1.0
